# v018_nt
# speedup vs baseline: 1.0061x; 1.0061x over previous
; __device__ __forceinline__ void convert_item(const float* __restrict__ src, int Ksz, int Nsz, u16* __restrict__ dst, int kb, int nb,
;                                              int mode, const int tid) {
;   const int n = nb * NTHR + tid;
;   if (n < Nsz) {
;     const float* sp = src + (size_t)(kb * 64) * Nsz + n;
;     float v[64];
; #pragma unroll
;     for (int j = 0; j < 64; ++j) v[j] = sp[(size_t)j * Nsz];
.Lcvm_nd:
	s_lshl_b32 s30, s25, 1
	s_lshl_b32 s31, s29, 1
	s_add_u32 s22, s22, s31
	s_addc_u32 s23, s23, 0
	s_lshl_b32 s6, s30, 3
	s_mov_b32 s7, 0
	v_mov_b32_e32 v86, s22
	v_mov_b32_e32 v87, s23
	v_mov_b32_e32 v88, s30
	v_mad_u64_u32 v[90:91], vcc, v84, v88, v[86:87]
	v_and_b32_e32 v0, 7, v164
	v_lshlrev_b32_e32 v0, 4, v0
	v_add_co_u32_e32 v84, vcc, v90, v0
	s_nop 1
	v_addc_co_u32_e32 v85, vcc, 0, v91, vcc
	v_lshlrev_b32_e32 v1, 2, v164
	v_lshrrev_b32_e32 v2, 6, v164
	v_mul_u32_u24_e32 v2, 0x2400, v2
	v_and_b32_e32 v3, 63, v164
	v_lshrrev_b32_e32 v89, 3, v3
	v_mul_u32_u24_e32 v89, 0x90, v89
	v_add3_u32 v89, v89, v0, v2
	v_mul_u32_u24_e32 v3, 0x90, v3
	v_add3_u32 v2, v2, v3, 32
	v_add_u32_e32 v3, 32, v89
	global_load_dword v4, v1, s[8:9] nt
	s_add_u32 s8, s8, s10
	s_addc_u32 s9, s9, 0
	global_load_dword v5, v1, s[8:9] nt
	s_add_u32 s8, s8, s10
	s_addc_u32 s9, s9, 0
	global_load_dword v6, v1, s[8:9] nt
	s_add_u32 s8, s8, s10
	s_addc_u32 s9, s9, 0
	global_load_dword v7, v1, s[8:9] nt
	s_add_u32 s8, s8, s10
	s_addc_u32 s9, s9, 0
	global_load_dword v8, v1, s[8:9] nt
	s_add_u32 s8, s8, s10
	s_addc_u32 s9, s9, 0
	global_load_dword v9, v1, s[8:9] nt
	s_add_u32 s8, s8, s10
	s_addc_u32 s9, s9, 0
	global_load_dword v10, v1, s[8:9] nt
	s_add_u32 s8, s8, s10
	s_addc_u32 s9, s9, 0
	global_load_dword v11, v1, s[8:9] nt
	s_add_u32 s8, s8, s10
	s_addc_u32 s9, s9, 0
	global_load_dword v12, v1, s[8:9] nt
	s_add_u32 s8, s8, s10
	s_addc_u32 s9, s9, 0
	global_load_dword v13, v1, s[8:9] nt
	s_add_u32 s8, s8, s10
	s_addc_u32 s9, s9, 0
	global_load_dword v14, v1, s[8:9] nt
	s_add_u32 s8, s8, s10
	s_addc_u32 s9, s9, 0
	global_load_dword v15, v1, s[8:9] nt
	s_add_u32 s8, s8, s10
	s_addc_u32 s9, s9, 0
	global_load_dword v16, v1, s[8:9] nt
	s_add_u32 s8, s8, s10
	s_addc_u32 s9, s9, 0
	global_load_dword v17, v1, s[8:9] nt
	s_add_u32 s8, s8, s10
	s_addc_u32 s9, s9, 0
	global_load_dword v18, v1, s[8:9] nt
	s_add_u32 s8, s8, s10
	s_addc_u32 s9, s9, 0
	global_load_dword v19, v1, s[8:9] nt
	s_add_u32 s8, s8, s10
	s_addc_u32 s9, s9, 0
	global_load_dword v20, v1, s[8:9] nt
	s_add_u32 s8, s8, s10
	s_addc_u32 s9, s9, 0
	global_load_dword v21, v1, s[8:9] nt
	s_add_u32 s8, s8, s10
	s_addc_u32 s9, s9, 0
	global_load_dword v22, v1, s[8:9] nt
	s_add_u32 s8, s8, s10
	s_addc_u32 s9, s9, 0
	global_load_dword v23, v1, s[8:9] nt
	s_add_u32 s8, s8, s10
	s_addc_u32 s9, s9, 0
	global_load_dword v24, v1, s[8:9] nt
	s_add_u32 s8, s8, s10
	s_addc_u32 s9, s9, 0
	global_load_dword v25, v1, s[8:9] nt
	s_add_u32 s8, s8, s10
	s_addc_u32 s9, s9, 0
	global_load_dword v26, v1, s[8:9] nt
	s_add_u32 s8, s8, s10
	s_addc_u32 s9, s9, 0
	global_load_dword v27, v1, s[8:9] nt
	s_add_u32 s8, s8, s10
	s_addc_u32 s9, s9, 0
	global_load_dword v28, v1, s[8:9] nt
	s_add_u32 s8, s8, s10
	s_addc_u32 s9, s9, 0
	global_load_dword v29, v1, s[8:9] nt
	s_add_u32 s8, s8, s10
	s_addc_u32 s9, s9, 0
	global_load_dword v30, v1, s[8:9] nt
	s_add_u32 s8, s8, s10
	s_addc_u32 s9, s9, 0
	global_load_dword v31, v1, s[8:9] nt
	s_add_u32 s8, s8, s10
	s_addc_u32 s9, s9, 0
	global_load_dword v32, v1, s[8:9] nt
	s_add_u32 s8, s8, s10
	s_addc_u32 s9, s9, 0
	global_load_dword v33, v1, s[8:9] nt
	s_add_u32 s8, s8, s10
	s_addc_u32 s9, s9, 0
	global_load_dword v34, v1, s[8:9] nt
	s_add_u32 s8, s8, s10
	s_addc_u32 s9, s9, 0
	global_load_dword v35, v1, s[8:9] nt
	s_add_u32 s8, s8, s10
	s_addc_u32 s9, s9, 0
	global_load_dword v36, v1, s[8:9] nt
	s_add_u32 s8, s8, s10
	s_addc_u32 s9, s9, 0
	global_load_dword v37, v1, s[8:9] nt
	s_add_u32 s8, s8, s10
	s_addc_u32 s9, s9, 0
	global_load_dword v38, v1, s[8:9] nt
	s_add_u32 s8, s8, s10
	s_addc_u32 s9, s9, 0
	global_load_dword v39, v1, s[8:9] nt
	s_add_u32 s8, s8, s10
	s_addc_u32 s9, s9, 0
	global_load_dword v40, v1, s[8:9] nt
	s_add_u32 s8, s8, s10
	s_addc_u32 s9, s9, 0
	global_load_dword v41, v1, s[8:9] nt
	s_add_u32 s8, s8, s10
	s_addc_u32 s9, s9, 0
	global_load_dword v42, v1, s[8:9] nt
	s_add_u32 s8, s8, s10
	s_addc_u32 s9, s9, 0
	global_load_dword v43, v1, s[8:9] nt
	s_add_u32 s8, s8, s10
	s_addc_u32 s9, s9, 0
	global_load_dword v44, v1, s[8:9] nt
	s_add_u32 s8, s8, s10
	s_addc_u32 s9, s9, 0
	global_load_dword v45, v1, s[8:9] nt
	s_add_u32 s8, s8, s10
	s_addc_u32 s9, s9, 0
	global_load_dword v46, v1, s[8:9] nt
	s_add_u32 s8, s8, s10
	s_addc_u32 s9, s9, 0
	global_load_dword v47, v1, s[8:9] nt
	s_add_u32 s8, s8, s10
	s_addc_u32 s9, s9, 0
	global_load_dword v48, v1, s[8:9] nt
	s_add_u32 s8, s8, s10
	s_addc_u32 s9, s9, 0
	global_load_dword v49, v1, s[8:9] nt
	s_add_u32 s8, s8, s10
	s_addc_u32 s9, s9, 0
	global_load_dword v50, v1, s[8:9] nt
	s_add_u32 s8, s8, s10
	s_addc_u32 s9, s9, 0
	global_load_dword v51, v1, s[8:9] nt
	s_add_u32 s8, s8, s10
	s_addc_u32 s9, s9, 0
	global_load_dword v52, v1, s[8:9] nt
	s_add_u32 s8, s8, s10
	s_addc_u32 s9, s9, 0
	global_load_dword v53, v1, s[8:9] nt
	s_add_u32 s8, s8, s10
	s_addc_u32 s9, s9, 0
	global_load_dword v54, v1, s[8:9] nt
	s_add_u32 s8, s8, s10
	s_addc_u32 s9, s9, 0
	global_load_dword v55, v1, s[8:9] nt
	s_add_u32 s8, s8, s10
	s_addc_u32 s9, s9, 0
	global_load_dword v56, v1, s[8:9] nt
	s_add_u32 s8, s8, s10
	s_addc_u32 s9, s9, 0
	global_load_dword v57, v1, s[8:9] nt
	s_add_u32 s8, s8, s10
	s_addc_u32 s9, s9, 0
	global_load_dword v58, v1, s[8:9] nt
	s_add_u32 s8, s8, s10
	s_addc_u32 s9, s9, 0
	global_load_dword v59, v1, s[8:9] nt
	s_add_u32 s8, s8, s10
	s_addc_u32 s9, s9, 0
	global_load_dword v60, v1, s[8:9] nt
	s_add_u32 s8, s8, s10
	s_addc_u32 s9, s9, 0
	global_load_dword v61, v1, s[8:9] nt
	s_add_u32 s8, s8, s10
	s_addc_u32 s9, s9, 0
	global_load_dword v62, v1, s[8:9] nt
	s_add_u32 s8, s8, s10
	s_addc_u32 s9, s9, 0
	global_load_dword v63, v1, s[8:9] nt
	s_add_u32 s8, s8, s10
	s_addc_u32 s9, s9, 0
	global_load_dword v64, v1, s[8:9] nt
	s_add_u32 s8, s8, s10
	s_addc_u32 s9, s9, 0
	global_load_dword v65, v1, s[8:9] nt
	s_add_u32 s8, s8, s10
	s_addc_u32 s9, s9, 0
	global_load_dword v66, v1, s[8:9] nt
	s_add_u32 s8, s8, s10
	s_addc_u32 s9, s9, 0
	global_load_dword v67, v1, s[8:9] nt
	s_add_u32 s8, s8, s10
	s_addc_u32 s9, s9, 0
	s_waitcnt vmcnt(32)
; __device__ __forceinline__ void convert_item(const float* __restrict__ src, int Ksz, int Nsz, u16* __restrict__ dst, int kb, int nb,
;                                              int mode, const int tid) {
;     ...
;     for (int j = 0; j < 64; ++j) v[j] = sp[(size_t)j * Nsz];
;     int nd = n;
;     if (mode == 1) {
;       int isg = n >= 1024, c = n & 1023;
;       nd = (c >> 7) * 256 + isg * 128 + (c & 127);
;     }
;     u32x4* d = reinterpret_cast<u32x4*>(dst + (size_t)nd * Ksz + kb * 64);
; #pragma unroll
;     for (int q = 0; q < 8; ++q) {
;       u32x4 o;
;       o.x = pack2(v[q * 8 + 0], v[q * 8 + 1]);
;       o.y = pack2(v[q * 8 + 2], v[q * 8 + 3]);
;       o.z = pack2(v[q * 8 + 4], v[q * 8 + 5]);
;       o.w = pack2(v[q * 8 + 6], v[q * 8 + 7]);
;       d[q] = o;
	v_cvt_pk_bf16_f32 v68, v4, v5
	v_cvt_pk_bf16_f32 v69, v6, v7
	v_cvt_pk_bf16_f32 v70, v8, v9
	v_cvt_pk_bf16_f32 v71, v10, v11
	v_cvt_pk_bf16_f32 v72, v12, v13
	v_cvt_pk_bf16_f32 v73, v14, v15
	v_cvt_pk_bf16_f32 v74, v16, v17
	v_cvt_pk_bf16_f32 v75, v18, v19
	v_cvt_pk_bf16_f32 v76, v20, v21
	v_cvt_pk_bf16_f32 v77, v22, v23
	v_cvt_pk_bf16_f32 v78, v24, v25
	v_cvt_pk_bf16_f32 v79, v26, v27
	v_cvt_pk_bf16_f32 v80, v28, v29
	v_cvt_pk_bf16_f32 v81, v30, v31
	v_cvt_pk_bf16_f32 v82, v32, v33
	v_cvt_pk_bf16_f32 v83, v34, v35
	ds_write_b128 v2, v[68:71] offset:0
	ds_write_b128 v2, v[72:75] offset:16
	ds_write_b128 v2, v[76:79] offset:32
	ds_write_b128 v2, v[80:83] offset:48
	global_load_dword v4, v1, s[8:9] nt
	s_add_u32 s8, s8, s10
	s_addc_u32 s9, s9, 0
	global_load_dword v5, v1, s[8:9] nt
	s_add_u32 s8, s8, s10
	s_addc_u32 s9, s9, 0
	global_load_dword v6, v1, s[8:9] nt
	s_add_u32 s8, s8, s10
	s_addc_u32 s9, s9, 0
	global_load_dword v7, v1, s[8:9] nt
	s_add_u32 s8, s8, s10
	s_addc_u32 s9, s9, 0
	global_load_dword v8, v1, s[8:9] nt
	s_add_u32 s8, s8, s10
	s_addc_u32 s9, s9, 0
	global_load_dword v9, v1, s[8:9] nt
	s_add_u32 s8, s8, s10
	s_addc_u32 s9, s9, 0
	global_load_dword v10, v1, s[8:9] nt
	s_add_u32 s8, s8, s10
	s_addc_u32 s9, s9, 0
	global_load_dword v11, v1, s[8:9] nt
	s_add_u32 s8, s8, s10
	s_addc_u32 s9, s9, 0
	global_load_dword v12, v1, s[8:9] nt
	s_add_u32 s8, s8, s10
	s_addc_u32 s9, s9, 0
	global_load_dword v13, v1, s[8:9] nt
	s_add_u32 s8, s8, s10
	s_addc_u32 s9, s9, 0
	global_load_dword v14, v1, s[8:9] nt
	s_add_u32 s8, s8, s10
	s_addc_u32 s9, s9, 0
	global_load_dword v15, v1, s[8:9] nt
	s_add_u32 s8, s8, s10
	s_addc_u32 s9, s9, 0
	global_load_dword v16, v1, s[8:9] nt
	s_add_u32 s8, s8, s10
	s_addc_u32 s9, s9, 0
	global_load_dword v17, v1, s[8:9] nt
	s_add_u32 s8, s8, s10
	s_addc_u32 s9, s9, 0
	global_load_dword v18, v1, s[8:9] nt
	s_add_u32 s8, s8, s10
	s_addc_u32 s9, s9, 0
	global_load_dword v19, v1, s[8:9] nt
	s_add_u32 s8, s8, s10
	s_addc_u32 s9, s9, 0
	global_load_dword v20, v1, s[8:9] nt
	s_add_u32 s8, s8, s10
	s_addc_u32 s9, s9, 0
	global_load_dword v21, v1, s[8:9] nt
	s_add_u32 s8, s8, s10
	s_addc_u32 s9, s9, 0
	global_load_dword v22, v1, s[8:9] nt
	s_add_u32 s8, s8, s10
	s_addc_u32 s9, s9, 0
	global_load_dword v23, v1, s[8:9] nt
	s_add_u32 s8, s8, s10
	s_addc_u32 s9, s9, 0
	global_load_dword v24, v1, s[8:9] nt
	s_add_u32 s8, s8, s10
	s_addc_u32 s9, s9, 0
	global_load_dword v25, v1, s[8:9] nt
	s_add_u32 s8, s8, s10
	s_addc_u32 s9, s9, 0
	global_load_dword v26, v1, s[8:9] nt
	s_add_u32 s8, s8, s10
	s_addc_u32 s9, s9, 0
	global_load_dword v27, v1, s[8:9] nt
	s_add_u32 s8, s8, s10
	s_addc_u32 s9, s9, 0
	global_load_dword v28, v1, s[8:9] nt
	s_add_u32 s8, s8, s10
	s_addc_u32 s9, s9, 0
	global_load_dword v29, v1, s[8:9] nt
	s_add_u32 s8, s8, s10
	s_addc_u32 s9, s9, 0
	global_load_dword v30, v1, s[8:9] nt
	s_add_u32 s8, s8, s10
	s_addc_u32 s9, s9, 0
	global_load_dword v31, v1, s[8:9] nt
	s_add_u32 s8, s8, s10
	s_addc_u32 s9, s9, 0
	global_load_dword v32, v1, s[8:9] nt
	s_add_u32 s8, s8, s10
	s_addc_u32 s9, s9, 0
	global_load_dword v33, v1, s[8:9] nt
	s_add_u32 s8, s8, s10
	s_addc_u32 s9, s9, 0
	global_load_dword v34, v1, s[8:9] nt
	s_add_u32 s8, s8, s10
	s_addc_u32 s9, s9, 0
	global_load_dword v35, v1, s[8:9] nt
	s_add_u32 s8, s8, s10
	s_addc_u32 s9, s9, 0
	s_waitcnt vmcnt(32)
	v_cvt_pk_bf16_f32 v100, v36, v37
	v_cvt_pk_bf16_f32 v101, v38, v39
	v_cvt_pk_bf16_f32 v102, v40, v41
	v_cvt_pk_bf16_f32 v103, v42, v43
	v_cvt_pk_bf16_f32 v104, v44, v45
	v_cvt_pk_bf16_f32 v105, v46, v47
	v_cvt_pk_bf16_f32 v106, v48, v49
	v_cvt_pk_bf16_f32 v107, v50, v51
	v_cvt_pk_bf16_f32 v108, v52, v53
	v_cvt_pk_bf16_f32 v109, v54, v55
	v_cvt_pk_bf16_f32 v110, v56, v57
	v_cvt_pk_bf16_f32 v111, v58, v59
	v_cvt_pk_bf16_f32 v112, v60, v61
	v_cvt_pk_bf16_f32 v113, v62, v63
	v_cvt_pk_bf16_f32 v114, v64, v65
	v_cvt_pk_bf16_f32 v115, v66, v67
	ds_write_b128 v2, v[100:103] offset:64
	ds_write_b128 v2, v[104:107] offset:80
	ds_write_b128 v2, v[108:111] offset:96
	ds_write_b128 v2, v[112:115] offset:112
	global_load_dword v36, v1, s[8:9] nt
	s_add_u32 s8, s8, s10
	s_addc_u32 s9, s9, 0
	global_load_dword v37, v1, s[8:9] nt
	s_add_u32 s8, s8, s10
	s_addc_u32 s9, s9, 0
	global_load_dword v38, v1, s[8:9] nt
	s_add_u32 s8, s8, s10
	s_addc_u32 s9, s9, 0
	global_load_dword v39, v1, s[8:9] nt
	s_add_u32 s8, s8, s10
	s_addc_u32 s9, s9, 0
	global_load_dword v40, v1, s[8:9] nt
	s_add_u32 s8, s8, s10
	s_addc_u32 s9, s9, 0
	global_load_dword v41, v1, s[8:9] nt
	s_add_u32 s8, s8, s10
	s_addc_u32 s9, s9, 0
	global_load_dword v42, v1, s[8:9] nt
	s_add_u32 s8, s8, s10
	s_addc_u32 s9, s9, 0
	global_load_dword v43, v1, s[8:9] nt
	s_add_u32 s8, s8, s10
	s_addc_u32 s9, s9, 0
	global_load_dword v44, v1, s[8:9] nt
	s_add_u32 s8, s8, s10
	s_addc_u32 s9, s9, 0
	global_load_dword v45, v1, s[8:9] nt
	s_add_u32 s8, s8, s10
	s_addc_u32 s9, s9, 0
	global_load_dword v46, v1, s[8:9] nt
	s_add_u32 s8, s8, s10
	s_addc_u32 s9, s9, 0
	global_load_dword v47, v1, s[8:9] nt
	s_add_u32 s8, s8, s10
	s_addc_u32 s9, s9, 0
	global_load_dword v48, v1, s[8:9] nt
	s_add_u32 s8, s8, s10
	s_addc_u32 s9, s9, 0
	global_load_dword v49, v1, s[8:9] nt
	s_add_u32 s8, s8, s10
	s_addc_u32 s9, s9, 0
	global_load_dword v50, v1, s[8:9] nt
	s_add_u32 s8, s8, s10
	s_addc_u32 s9, s9, 0
	global_load_dword v51, v1, s[8:9] nt
	s_add_u32 s8, s8, s10
	s_addc_u32 s9, s9, 0
	global_load_dword v52, v1, s[8:9] nt
	s_add_u32 s8, s8, s10
	s_addc_u32 s9, s9, 0
	global_load_dword v53, v1, s[8:9] nt
	s_add_u32 s8, s8, s10
	s_addc_u32 s9, s9, 0
	global_load_dword v54, v1, s[8:9] nt
	s_add_u32 s8, s8, s10
	s_addc_u32 s9, s9, 0
	global_load_dword v55, v1, s[8:9] nt
	s_add_u32 s8, s8, s10
	s_addc_u32 s9, s9, 0
	global_load_dword v56, v1, s[8:9] nt
	s_add_u32 s8, s8, s10
	s_addc_u32 s9, s9, 0
	global_load_dword v57, v1, s[8:9] nt
	s_add_u32 s8, s8, s10
	s_addc_u32 s9, s9, 0
	global_load_dword v58, v1, s[8:9] nt
	s_add_u32 s8, s8, s10
	s_addc_u32 s9, s9, 0
	global_load_dword v59, v1, s[8:9] nt
	s_add_u32 s8, s8, s10
	s_addc_u32 s9, s9, 0
	global_load_dword v60, v1, s[8:9] nt
	s_add_u32 s8, s8, s10
	s_addc_u32 s9, s9, 0
	global_load_dword v61, v1, s[8:9] nt
	s_add_u32 s8, s8, s10
	s_addc_u32 s9, s9, 0
	global_load_dword v62, v1, s[8:9] nt
	s_add_u32 s8, s8, s10
	s_addc_u32 s9, s9, 0
	global_load_dword v63, v1, s[8:9] nt
	s_add_u32 s8, s8, s10
	s_addc_u32 s9, s9, 0
	global_load_dword v64, v1, s[8:9] nt
	s_add_u32 s8, s8, s10
	s_addc_u32 s9, s9, 0
	global_load_dword v65, v1, s[8:9] nt
	s_add_u32 s8, s8, s10
	s_addc_u32 s9, s9, 0
	global_load_dword v66, v1, s[8:9] nt
	s_add_u32 s8, s8, s10
	s_addc_u32 s9, s9, 0
	global_load_dword v67, v1, s[8:9] nt
	s_add_u32 s8, s8, s10
	s_addc_u32 s9, s9, 0
	v_mov_b32_e32 v86, v84
	v_mov_b32_e32 v87, v85
	ds_read_b128 v[116:119], v3 offset:0
	ds_read_b128 v[120:123], v3 offset:1152
	ds_read_b128 v[124:127], v3 offset:2304
	ds_read_b128 v[128:131], v3 offset:3456
	s_waitcnt lgkmcnt(0)
; __device__ __forceinline__ void convert_item(const float* __restrict__ src, int Ksz, int Nsz, u16* __restrict__ dst, int kb, int nb,
;                                              int mode, const int tid) {
;     ...
;     u32x4* d = reinterpret_cast<u32x4*>(dst + (size_t)nd * Ksz + kb * 64);
; #pragma unroll
;     for (int q = 0; q < 8; ++q) {
;       u32x4 o;
;       o.x = pack2(v[q * 8 + 0], v[q * 8 + 1]);
;       o.y = pack2(v[q * 8 + 2], v[q * 8 + 3]);
;       o.z = pack2(v[q * 8 + 4], v[q * 8 + 5]);
;       o.w = pack2(v[q * 8 + 6], v[q * 8 + 7]);
;       d[q] = o;
	global_store_dwordx4 v[86:87], v[116:119], off offset:0
	v_lshl_add_u64 v[86:87], v[86:87], 0, s[6:7]
	global_store_dwordx4 v[86:87], v[120:123], off offset:0
	v_lshl_add_u64 v[86:87], v[86:87], 0, s[6:7]
	global_store_dwordx4 v[86:87], v[124:127], off offset:0
	v_lshl_add_u64 v[86:87], v[86:87], 0, s[6:7]
	global_store_dwordx4 v[86:87], v[128:131], off offset:0
	v_lshl_add_u64 v[86:87], v[86:87], 0, s[6:7]
	ds_read_b128 v[116:119], v3 offset:4608
	ds_read_b128 v[120:123], v3 offset:5760
	ds_read_b128 v[124:127], v3 offset:6912
	ds_read_b128 v[128:131], v3 offset:8064
	s_waitcnt lgkmcnt(0)
	global_store_dwordx4 v[86:87], v[116:119], off offset:0
	v_lshl_add_u64 v[86:87], v[86:87], 0, s[6:7]
	global_store_dwordx4 v[86:87], v[120:123], off offset:0
	v_lshl_add_u64 v[86:87], v[86:87], 0, s[6:7]
	global_store_dwordx4 v[86:87], v[124:127], off offset:0
	v_lshl_add_u64 v[86:87], v[86:87], 0, s[6:7]
	global_store_dwordx4 v[86:87], v[128:131], off offset:0
	v_lshl_add_u64 v[86:87], v[86:87], 0, s[6:7]
	s_waitcnt vmcnt(40)
	v_cvt_pk_bf16_f32 v68, v4, v5
	v_cvt_pk_bf16_f32 v69, v6, v7
	v_cvt_pk_bf16_f32 v70, v8, v9
	v_cvt_pk_bf16_f32 v71, v10, v11
	v_cvt_pk_bf16_f32 v72, v12, v13
	v_cvt_pk_bf16_f32 v73, v14, v15
	v_cvt_pk_bf16_f32 v74, v16, v17
	v_cvt_pk_bf16_f32 v75, v18, v19
	v_cvt_pk_bf16_f32 v76, v20, v21
	v_cvt_pk_bf16_f32 v77, v22, v23
	v_cvt_pk_bf16_f32 v78, v24, v25
	v_cvt_pk_bf16_f32 v79, v26, v27
	v_cvt_pk_bf16_f32 v80, v28, v29
	v_cvt_pk_bf16_f32 v81, v30, v31
	v_cvt_pk_bf16_f32 v82, v32, v33
	v_cvt_pk_bf16_f32 v83, v34, v35
	ds_write_b128 v2, v[68:71] offset:0
	ds_write_b128 v2, v[72:75] offset:16
	ds_write_b128 v2, v[76:79] offset:32
	ds_write_b128 v2, v[80:83] offset:48
	global_load_dword v4, v1, s[8:9] nt
	s_add_u32 s8, s8, s10
	s_addc_u32 s9, s9, 0
	global_load_dword v5, v1, s[8:9] nt
	s_add_u32 s8, s8, s10
	s_addc_u32 s9, s9, 0
	global_load_dword v6, v1, s[8:9] nt
	s_add_u32 s8, s8, s10
	s_addc_u32 s9, s9, 0
	global_load_dword v7, v1, s[8:9] nt
	s_add_u32 s8, s8, s10
	s_addc_u32 s9, s9, 0
	global_load_dword v8, v1, s[8:9] nt
	s_add_u32 s8, s8, s10
	s_addc_u32 s9, s9, 0
	global_load_dword v9, v1, s[8:9] nt
	s_add_u32 s8, s8, s10
	s_addc_u32 s9, s9, 0
	global_load_dword v10, v1, s[8:9] nt
	s_add_u32 s8, s8, s10
	s_addc_u32 s9, s9, 0
	global_load_dword v11, v1, s[8:9] nt
	s_add_u32 s8, s8, s10
	s_addc_u32 s9, s9, 0
	global_load_dword v12, v1, s[8:9] nt
	s_add_u32 s8, s8, s10
	s_addc_u32 s9, s9, 0
	global_load_dword v13, v1, s[8:9] nt
	s_add_u32 s8, s8, s10
	s_addc_u32 s9, s9, 0
	global_load_dword v14, v1, s[8:9] nt
	s_add_u32 s8, s8, s10
	s_addc_u32 s9, s9, 0
	global_load_dword v15, v1, s[8:9] nt
	s_add_u32 s8, s8, s10
	s_addc_u32 s9, s9, 0
	global_load_dword v16, v1, s[8:9] nt
	s_add_u32 s8, s8, s10
	s_addc_u32 s9, s9, 0
	global_load_dword v17, v1, s[8:9] nt
	s_add_u32 s8, s8, s10
	s_addc_u32 s9, s9, 0
	global_load_dword v18, v1, s[8:9] nt
	s_add_u32 s8, s8, s10
	s_addc_u32 s9, s9, 0
	global_load_dword v19, v1, s[8:9] nt
	s_add_u32 s8, s8, s10
	s_addc_u32 s9, s9, 0
	global_load_dword v20, v1, s[8:9] nt
	s_add_u32 s8, s8, s10
	s_addc_u32 s9, s9, 0
	global_load_dword v21, v1, s[8:9] nt
	s_add_u32 s8, s8, s10
	s_addc_u32 s9, s9, 0
	global_load_dword v22, v1, s[8:9] nt
	s_add_u32 s8, s8, s10
	s_addc_u32 s9, s9, 0
	global_load_dword v23, v1, s[8:9] nt
	s_add_u32 s8, s8, s10
	s_addc_u32 s9, s9, 0
	global_load_dword v24, v1, s[8:9] nt
	s_add_u32 s8, s8, s10
	s_addc_u32 s9, s9, 0
	global_load_dword v25, v1, s[8:9] nt
	s_add_u32 s8, s8, s10
	s_addc_u32 s9, s9, 0
	global_load_dword v26, v1, s[8:9] nt
	s_add_u32 s8, s8, s10
	s_addc_u32 s9, s9, 0
	global_load_dword v27, v1, s[8:9] nt
	s_add_u32 s8, s8, s10
	s_addc_u32 s9, s9, 0
	global_load_dword v28, v1, s[8:9] nt
	s_add_u32 s8, s8, s10
	s_addc_u32 s9, s9, 0
	global_load_dword v29, v1, s[8:9] nt
	s_add_u32 s8, s8, s10
	s_addc_u32 s9, s9, 0
	global_load_dword v30, v1, s[8:9] nt
	s_add_u32 s8, s8, s10
	s_addc_u32 s9, s9, 0
	global_load_dword v31, v1, s[8:9] nt
	s_add_u32 s8, s8, s10
	s_addc_u32 s9, s9, 0
	global_load_dword v32, v1, s[8:9] nt
	s_add_u32 s8, s8, s10
	s_addc_u32 s9, s9, 0
	global_load_dword v33, v1, s[8:9] nt
	s_add_u32 s8, s8, s10
	s_addc_u32 s9, s9, 0
	global_load_dword v34, v1, s[8:9] nt
	s_add_u32 s8, s8, s10
	s_addc_u32 s9, s9, 0
	global_load_dword v35, v1, s[8:9] nt
	s_add_u32 s8, s8, s10
	s_addc_u32 s9, s9, 0
	s_waitcnt vmcnt(40)
; __device__ __forceinline__ void convert_item(const float* __restrict__ src, int Ksz, int Nsz, u16* __restrict__ dst, int kb, int nb,
;                                              int mode, const int tid) {
;     ...
; #pragma unroll
;     for (int j = 0; j < 64; ++j) v[j] = sp[(size_t)j * Nsz];
;     int nd = n;
;     if (mode == 1) {
;       int isg = n >= 1024, c = n & 1023;
;       nd = (c >> 7) * 256 + isg * 128 + (c & 127);
;     }
;     u32x4* d = reinterpret_cast<u32x4*>(dst + (size_t)nd * Ksz + kb * 64);
; #pragma unroll
;     for (int q = 0; q < 8; ++q) {
;       u32x4 o;
;       o.x = pack2(v[q * 8 + 0], v[q * 8 + 1]);
;       o.y = pack2(v[q * 8 + 2], v[q * 8 + 3]);
;       o.z = pack2(v[q * 8 + 4], v[q * 8 + 5]);
;       o.w = pack2(v[q * 8 + 6], v[q * 8 + 7]);
;       d[q] = o;
;     }
	v_cvt_pk_bf16_f32 v100, v36, v37
	v_cvt_pk_bf16_f32 v101, v38, v39
	v_cvt_pk_bf16_f32 v102, v40, v41
	v_cvt_pk_bf16_f32 v103, v42, v43
	v_cvt_pk_bf16_f32 v104, v44, v45
	v_cvt_pk_bf16_f32 v105, v46, v47
	v_cvt_pk_bf16_f32 v106, v48, v49
	v_cvt_pk_bf16_f32 v107, v50, v51
	v_cvt_pk_bf16_f32 v108, v52, v53
	v_cvt_pk_bf16_f32 v109, v54, v55
	v_cvt_pk_bf16_f32 v110, v56, v57
	v_cvt_pk_bf16_f32 v111, v58, v59
	v_cvt_pk_bf16_f32 v112, v60, v61
	v_cvt_pk_bf16_f32 v113, v62, v63
	v_cvt_pk_bf16_f32 v114, v64, v65
	v_cvt_pk_bf16_f32 v115, v66, v67
	ds_write_b128 v2, v[100:103] offset:64
	ds_write_b128 v2, v[104:107] offset:80
	ds_write_b128 v2, v[108:111] offset:96
	ds_write_b128 v2, v[112:115] offset:112
	global_load_dword v36, v1, s[8:9] nt
	s_add_u32 s8, s8, s10
	s_addc_u32 s9, s9, 0
	global_load_dword v37, v1, s[8:9] nt
	s_add_u32 s8, s8, s10
	s_addc_u32 s9, s9, 0
	global_load_dword v38, v1, s[8:9] nt
	s_add_u32 s8, s8, s10
	s_addc_u32 s9, s9, 0
	global_load_dword v39, v1, s[8:9] nt
	s_add_u32 s8, s8, s10
	s_addc_u32 s9, s9, 0
	global_load_dword v40, v1, s[8:9] nt
	s_add_u32 s8, s8, s10
	s_addc_u32 s9, s9, 0
	global_load_dword v41, v1, s[8:9] nt
	s_add_u32 s8, s8, s10
	s_addc_u32 s9, s9, 0
	global_load_dword v42, v1, s[8:9] nt
	s_add_u32 s8, s8, s10
	s_addc_u32 s9, s9, 0
	global_load_dword v43, v1, s[8:9] nt
	s_add_u32 s8, s8, s10
	s_addc_u32 s9, s9, 0
	global_load_dword v44, v1, s[8:9] nt
	s_add_u32 s8, s8, s10
	s_addc_u32 s9, s9, 0
	global_load_dword v45, v1, s[8:9] nt
	s_add_u32 s8, s8, s10
	s_addc_u32 s9, s9, 0
	global_load_dword v46, v1, s[8:9] nt
	s_add_u32 s8, s8, s10
	s_addc_u32 s9, s9, 0
	global_load_dword v47, v1, s[8:9] nt
	s_add_u32 s8, s8, s10
	s_addc_u32 s9, s9, 0
	global_load_dword v48, v1, s[8:9] nt
	s_add_u32 s8, s8, s10
	s_addc_u32 s9, s9, 0
	global_load_dword v49, v1, s[8:9] nt
	s_add_u32 s8, s8, s10
	s_addc_u32 s9, s9, 0
	global_load_dword v50, v1, s[8:9] nt
	s_add_u32 s8, s8, s10
	s_addc_u32 s9, s9, 0
	global_load_dword v51, v1, s[8:9] nt
	s_add_u32 s8, s8, s10
	s_addc_u32 s9, s9, 0
	global_load_dword v52, v1, s[8:9] nt
	s_add_u32 s8, s8, s10
	s_addc_u32 s9, s9, 0
	global_load_dword v53, v1, s[8:9] nt
	s_add_u32 s8, s8, s10
	s_addc_u32 s9, s9, 0
	global_load_dword v54, v1, s[8:9] nt
	s_add_u32 s8, s8, s10
	s_addc_u32 s9, s9, 0
	global_load_dword v55, v1, s[8:9] nt
	s_add_u32 s8, s8, s10
	s_addc_u32 s9, s9, 0
	global_load_dword v56, v1, s[8:9] nt
	s_add_u32 s8, s8, s10
	s_addc_u32 s9, s9, 0
	global_load_dword v57, v1, s[8:9] nt
	s_add_u32 s8, s8, s10
	s_addc_u32 s9, s9, 0
	global_load_dword v58, v1, s[8:9] nt
	s_add_u32 s8, s8, s10
	s_addc_u32 s9, s9, 0
	global_load_dword v59, v1, s[8:9] nt
	s_add_u32 s8, s8, s10
	s_addc_u32 s9, s9, 0
	global_load_dword v60, v1, s[8:9] nt
	s_add_u32 s8, s8, s10
	s_addc_u32 s9, s9, 0
	global_load_dword v61, v1, s[8:9] nt
	s_add_u32 s8, s8, s10
	s_addc_u32 s9, s9, 0
	global_load_dword v62, v1, s[8:9] nt
	s_add_u32 s8, s8, s10
	s_addc_u32 s9, s9, 0
	global_load_dword v63, v1, s[8:9] nt
	s_add_u32 s8, s8, s10
	s_addc_u32 s9, s9, 0
	global_load_dword v64, v1, s[8:9] nt
	s_add_u32 s8, s8, s10
	s_addc_u32 s9, s9, 0
	global_load_dword v65, v1, s[8:9] nt
	s_add_u32 s8, s8, s10
	s_addc_u32 s9, s9, 0
	global_load_dword v66, v1, s[8:9] nt
	s_add_u32 s8, s8, s10
	s_addc_u32 s9, s9, 0
	global_load_dword v67, v1, s[8:9] nt
	s_add_u32 s8, s8, s10
	s_addc_u32 s9, s9, 0
	v_mov_b32_e32 v86, v84
	v_mov_b32_e32 v87, v85
	ds_read_b128 v[116:119], v3 offset:0
	ds_read_b128 v[120:123], v3 offset:1152
	ds_read_b128 v[124:127], v3 offset:2304
	ds_read_b128 v[128:131], v3 offset:3456
	s_waitcnt lgkmcnt(0)
	global_store_dwordx4 v[86:87], v[116:119], off offset:128
	v_lshl_add_u64 v[86:87], v[86:87], 0, s[6:7]
	global_store_dwordx4 v[86:87], v[120:123], off offset:128
	v_lshl_add_u64 v[86:87], v[86:87], 0, s[6:7]
	global_store_dwordx4 v[86:87], v[124:127], off offset:128
	v_lshl_add_u64 v[86:87], v[86:87], 0, s[6:7]
	global_store_dwordx4 v[86:87], v[128:131], off offset:128
	v_lshl_add_u64 v[86:87], v[86:87], 0, s[6:7]
	ds_read_b128 v[116:119], v3 offset:4608
	ds_read_b128 v[120:123], v3 offset:5760
	ds_read_b128 v[124:127], v3 offset:6912
	ds_read_b128 v[128:131], v3 offset:8064
	s_waitcnt lgkmcnt(0)
	global_store_dwordx4 v[86:87], v[116:119], off offset:128
	v_lshl_add_u64 v[86:87], v[86:87], 0, s[6:7]
	global_store_dwordx4 v[86:87], v[120:123], off offset:128
	v_lshl_add_u64 v[86:87], v[86:87], 0, s[6:7]
	global_store_dwordx4 v[86:87], v[124:127], off offset:128
	v_lshl_add_u64 v[86:87], v[86:87], 0, s[6:7]
	global_store_dwordx4 v[86:87], v[128:131], off offset:128
	v_lshl_add_u64 v[86:87], v[86:87], 0, s[6:7]
	s_waitcnt vmcnt(40)
; __device__ __forceinline__ void convert_item(const float* __restrict__ src, int Ksz, int Nsz, u16* __restrict__ dst, int kb, int nb,
;                                              int mode, const int tid) {
;     ...
; #pragma unroll
;     for (int j = 0; j < 64; ++j) v[j] = sp[(size_t)j * Nsz];
;     int nd = n;
;     if (mode == 1) {
;       int isg = n >= 1024, c = n & 1023;
;       nd = (c >> 7) * 256 + isg * 128 + (c & 127);
;     }
;     u32x4* d = reinterpret_cast<u32x4*>(dst + (size_t)nd * Ksz + kb * 64);
; #pragma unroll
;     for (int q = 0; q < 8; ++q) {
;       u32x4 o;
;       o.x = pack2(v[q * 8 + 0], v[q * 8 + 1]);
;       o.y = pack2(v[q * 8 + 2], v[q * 8 + 3]);
;       o.z = pack2(v[q * 8 + 4], v[q * 8 + 5]);
;       o.w = pack2(v[q * 8 + 6], v[q * 8 + 7]);
;       d[q] = o;
;     }
	v_cvt_pk_bf16_f32 v68, v4, v5
	v_cvt_pk_bf16_f32 v69, v6, v7
	v_cvt_pk_bf16_f32 v70, v8, v9
	v_cvt_pk_bf16_f32 v71, v10, v11
	v_cvt_pk_bf16_f32 v72, v12, v13
	v_cvt_pk_bf16_f32 v73, v14, v15
	v_cvt_pk_bf16_f32 v74, v16, v17
	v_cvt_pk_bf16_f32 v75, v18, v19
	v_cvt_pk_bf16_f32 v76, v20, v21
	v_cvt_pk_bf16_f32 v77, v22, v23
	v_cvt_pk_bf16_f32 v78, v24, v25
	v_cvt_pk_bf16_f32 v79, v26, v27
	v_cvt_pk_bf16_f32 v80, v28, v29
	v_cvt_pk_bf16_f32 v81, v30, v31
	v_cvt_pk_bf16_f32 v82, v32, v33
	v_cvt_pk_bf16_f32 v83, v34, v35
	ds_write_b128 v2, v[68:71] offset:0
	ds_write_b128 v2, v[72:75] offset:16
	ds_write_b128 v2, v[76:79] offset:32
	ds_write_b128 v2, v[80:83] offset:48
	global_load_dword v4, v1, s[8:9] nt
	s_add_u32 s8, s8, s10
	s_addc_u32 s9, s9, 0
	global_load_dword v5, v1, s[8:9] nt
	s_add_u32 s8, s8, s10
	s_addc_u32 s9, s9, 0
	global_load_dword v6, v1, s[8:9] nt
	s_add_u32 s8, s8, s10
	s_addc_u32 s9, s9, 0
	global_load_dword v7, v1, s[8:9] nt
	s_add_u32 s8, s8, s10
	s_addc_u32 s9, s9, 0
	global_load_dword v8, v1, s[8:9] nt
	s_add_u32 s8, s8, s10
	s_addc_u32 s9, s9, 0
	global_load_dword v9, v1, s[8:9] nt
	s_add_u32 s8, s8, s10
	s_addc_u32 s9, s9, 0
	global_load_dword v10, v1, s[8:9] nt
	s_add_u32 s8, s8, s10
	s_addc_u32 s9, s9, 0
	global_load_dword v11, v1, s[8:9] nt
	s_add_u32 s8, s8, s10
	s_addc_u32 s9, s9, 0
	global_load_dword v12, v1, s[8:9] nt
	s_add_u32 s8, s8, s10
	s_addc_u32 s9, s9, 0
	global_load_dword v13, v1, s[8:9] nt
	s_add_u32 s8, s8, s10
	s_addc_u32 s9, s9, 0
	global_load_dword v14, v1, s[8:9] nt
	s_add_u32 s8, s8, s10
	s_addc_u32 s9, s9, 0
	global_load_dword v15, v1, s[8:9] nt
	s_add_u32 s8, s8, s10
	s_addc_u32 s9, s9, 0
	global_load_dword v16, v1, s[8:9] nt
	s_add_u32 s8, s8, s10
	s_addc_u32 s9, s9, 0
	global_load_dword v17, v1, s[8:9] nt
	s_add_u32 s8, s8, s10
	s_addc_u32 s9, s9, 0
	global_load_dword v18, v1, s[8:9] nt
	s_add_u32 s8, s8, s10
	s_addc_u32 s9, s9, 0
	global_load_dword v19, v1, s[8:9] nt
	s_add_u32 s8, s8, s10
	s_addc_u32 s9, s9, 0
	global_load_dword v20, v1, s[8:9] nt
	s_add_u32 s8, s8, s10
	s_addc_u32 s9, s9, 0
	global_load_dword v21, v1, s[8:9] nt
	s_add_u32 s8, s8, s10
	s_addc_u32 s9, s9, 0
	global_load_dword v22, v1, s[8:9] nt
	s_add_u32 s8, s8, s10
	s_addc_u32 s9, s9, 0
	global_load_dword v23, v1, s[8:9] nt
	s_add_u32 s8, s8, s10
	s_addc_u32 s9, s9, 0
	global_load_dword v24, v1, s[8:9] nt
	s_add_u32 s8, s8, s10
	s_addc_u32 s9, s9, 0
	global_load_dword v25, v1, s[8:9] nt
	s_add_u32 s8, s8, s10
	s_addc_u32 s9, s9, 0
	global_load_dword v26, v1, s[8:9] nt
	s_add_u32 s8, s8, s10
	s_addc_u32 s9, s9, 0
	global_load_dword v27, v1, s[8:9] nt
	s_add_u32 s8, s8, s10
	s_addc_u32 s9, s9, 0
	global_load_dword v28, v1, s[8:9] nt
	s_add_u32 s8, s8, s10
	s_addc_u32 s9, s9, 0
	global_load_dword v29, v1, s[8:9] nt
	s_add_u32 s8, s8, s10
	s_addc_u32 s9, s9, 0
	global_load_dword v30, v1, s[8:9] nt
	s_add_u32 s8, s8, s10
	s_addc_u32 s9, s9, 0
	global_load_dword v31, v1, s[8:9] nt
	s_add_u32 s8, s8, s10
	s_addc_u32 s9, s9, 0
	global_load_dword v32, v1, s[8:9] nt
	s_add_u32 s8, s8, s10
	s_addc_u32 s9, s9, 0
	global_load_dword v33, v1, s[8:9] nt
	s_add_u32 s8, s8, s10
	s_addc_u32 s9, s9, 0
	global_load_dword v34, v1, s[8:9] nt
	s_add_u32 s8, s8, s10
	s_addc_u32 s9, s9, 0
	global_load_dword v35, v1, s[8:9] nt
	s_add_u32 s8, s8, s10
	s_addc_u32 s9, s9, 0
	s_waitcnt vmcnt(40)
	v_cvt_pk_bf16_f32 v100, v36, v37
	v_cvt_pk_bf16_f32 v101, v38, v39
	v_cvt_pk_bf16_f32 v102, v40, v41
	v_cvt_pk_bf16_f32 v103, v42, v43
	v_cvt_pk_bf16_f32 v104, v44, v45
	v_cvt_pk_bf16_f32 v105, v46, v47
	v_cvt_pk_bf16_f32 v106, v48, v49
	v_cvt_pk_bf16_f32 v107, v50, v51
	v_cvt_pk_bf16_f32 v108, v52, v53
	v_cvt_pk_bf16_f32 v109, v54, v55
	v_cvt_pk_bf16_f32 v110, v56, v57
	v_cvt_pk_bf16_f32 v111, v58, v59
	v_cvt_pk_bf16_f32 v112, v60, v61
	v_cvt_pk_bf16_f32 v113, v62, v63
	v_cvt_pk_bf16_f32 v114, v64, v65
	v_cvt_pk_bf16_f32 v115, v66, v67
	ds_write_b128 v2, v[100:103] offset:64
	ds_write_b128 v2, v[104:107] offset:80
	ds_write_b128 v2, v[108:111] offset:96
	ds_write_b128 v2, v[112:115] offset:112
	global_load_dword v36, v1, s[8:9] nt
	s_add_u32 s8, s8, s10
	s_addc_u32 s9, s9, 0
	global_load_dword v37, v1, s[8:9] nt
	s_add_u32 s8, s8, s10
	s_addc_u32 s9, s9, 0
	global_load_dword v38, v1, s[8:9] nt
	s_add_u32 s8, s8, s10
	s_addc_u32 s9, s9, 0
	global_load_dword v39, v1, s[8:9] nt
	s_add_u32 s8, s8, s10
	s_addc_u32 s9, s9, 0
	global_load_dword v40, v1, s[8:9] nt
	s_add_u32 s8, s8, s10
	s_addc_u32 s9, s9, 0
	global_load_dword v41, v1, s[8:9] nt
	s_add_u32 s8, s8, s10
	s_addc_u32 s9, s9, 0
	global_load_dword v42, v1, s[8:9] nt
	s_add_u32 s8, s8, s10
	s_addc_u32 s9, s9, 0
	global_load_dword v43, v1, s[8:9] nt
	s_add_u32 s8, s8, s10
	s_addc_u32 s9, s9, 0
	global_load_dword v44, v1, s[8:9] nt
	s_add_u32 s8, s8, s10
	s_addc_u32 s9, s9, 0
	global_load_dword v45, v1, s[8:9] nt
	s_add_u32 s8, s8, s10
	s_addc_u32 s9, s9, 0
	global_load_dword v46, v1, s[8:9] nt
	s_add_u32 s8, s8, s10
	s_addc_u32 s9, s9, 0
	global_load_dword v47, v1, s[8:9] nt
	s_add_u32 s8, s8, s10
	s_addc_u32 s9, s9, 0
	global_load_dword v48, v1, s[8:9] nt
	s_add_u32 s8, s8, s10
	s_addc_u32 s9, s9, 0
	global_load_dword v49, v1, s[8:9] nt
	s_add_u32 s8, s8, s10
	s_addc_u32 s9, s9, 0
	global_load_dword v50, v1, s[8:9] nt
	s_add_u32 s8, s8, s10
	s_addc_u32 s9, s9, 0
	global_load_dword v51, v1, s[8:9] nt
	s_add_u32 s8, s8, s10
	s_addc_u32 s9, s9, 0
	global_load_dword v52, v1, s[8:9] nt
	s_add_u32 s8, s8, s10
	s_addc_u32 s9, s9, 0
	global_load_dword v53, v1, s[8:9] nt
	s_add_u32 s8, s8, s10
	s_addc_u32 s9, s9, 0
	global_load_dword v54, v1, s[8:9] nt
	s_add_u32 s8, s8, s10
	s_addc_u32 s9, s9, 0
	global_load_dword v55, v1, s[8:9] nt
	s_add_u32 s8, s8, s10
	s_addc_u32 s9, s9, 0
	global_load_dword v56, v1, s[8:9] nt
	s_add_u32 s8, s8, s10
	s_addc_u32 s9, s9, 0
	global_load_dword v57, v1, s[8:9] nt
	s_add_u32 s8, s8, s10
	s_addc_u32 s9, s9, 0
	global_load_dword v58, v1, s[8:9] nt
	s_add_u32 s8, s8, s10
	s_addc_u32 s9, s9, 0
	global_load_dword v59, v1, s[8:9] nt
	s_add_u32 s8, s8, s10
	s_addc_u32 s9, s9, 0
	global_load_dword v60, v1, s[8:9] nt
	s_add_u32 s8, s8, s10
	s_addc_u32 s9, s9, 0
	global_load_dword v61, v1, s[8:9] nt
	s_add_u32 s8, s8, s10
	s_addc_u32 s9, s9, 0
	global_load_dword v62, v1, s[8:9] nt
	s_add_u32 s8, s8, s10
	s_addc_u32 s9, s9, 0
	global_load_dword v63, v1, s[8:9] nt
	s_add_u32 s8, s8, s10
	s_addc_u32 s9, s9, 0
	global_load_dword v64, v1, s[8:9] nt
	s_add_u32 s8, s8, s10
	s_addc_u32 s9, s9, 0
	global_load_dword v65, v1, s[8:9] nt
	s_add_u32 s8, s8, s10
	s_addc_u32 s9, s9, 0
	global_load_dword v66, v1, s[8:9] nt
	s_add_u32 s8, s8, s10
	s_addc_u32 s9, s9, 0
	global_load_dword v67, v1, s[8:9] nt
	s_add_u32 s8, s8, s10
	s_addc_u32 s9, s9, 0
	v_mov_b32_e32 v86, v84
	v_mov_b32_e32 v87, v85
	ds_read_b128 v[116:119], v3 offset:0
	ds_read_b128 v[120:123], v3 offset:1152
	ds_read_b128 v[124:127], v3 offset:2304
	ds_read_b128 v[128:131], v3 offset:3456
	s_waitcnt lgkmcnt(0)
; __device__ __forceinline__ void convert_item(const float* __restrict__ src, int Ksz, int Nsz, u16* __restrict__ dst, int kb, int nb,
;                                              int mode, const int tid) {
;     ...
; #pragma unroll
;     for (int j = 0; j < 64; ++j) v[j] = sp[(size_t)j * Nsz];
;     int nd = n;
;     if (mode == 1) {
;       int isg = n >= 1024, c = n & 1023;
;       nd = (c >> 7) * 256 + isg * 128 + (c & 127);
;     }
;     u32x4* d = reinterpret_cast<u32x4*>(dst + (size_t)nd * Ksz + kb * 64);
; #pragma unroll
;     for (int q = 0; q < 8; ++q) {
;       u32x4 o;
;       o.x = pack2(v[q * 8 + 0], v[q * 8 + 1]);
;       o.y = pack2(v[q * 8 + 2], v[q * 8 + 3]);
;       o.z = pack2(v[q * 8 + 4], v[q * 8 + 5]);
;       o.w = pack2(v[q * 8 + 6], v[q * 8 + 7]);
;       d[q] = o;
;     }
	global_store_dwordx4 v[86:87], v[116:119], off offset:256
	v_lshl_add_u64 v[86:87], v[86:87], 0, s[6:7]
	global_store_dwordx4 v[86:87], v[120:123], off offset:256
	v_lshl_add_u64 v[86:87], v[86:87], 0, s[6:7]
	global_store_dwordx4 v[86:87], v[124:127], off offset:256
	v_lshl_add_u64 v[86:87], v[86:87], 0, s[6:7]
	global_store_dwordx4 v[86:87], v[128:131], off offset:256
	v_lshl_add_u64 v[86:87], v[86:87], 0, s[6:7]
	ds_read_b128 v[116:119], v3 offset:4608
	ds_read_b128 v[120:123], v3 offset:5760
	ds_read_b128 v[124:127], v3 offset:6912
	ds_read_b128 v[128:131], v3 offset:8064
	s_waitcnt lgkmcnt(0)
	global_store_dwordx4 v[86:87], v[116:119], off offset:256
	v_lshl_add_u64 v[86:87], v[86:87], 0, s[6:7]
	global_store_dwordx4 v[86:87], v[120:123], off offset:256
	v_lshl_add_u64 v[86:87], v[86:87], 0, s[6:7]
	global_store_dwordx4 v[86:87], v[124:127], off offset:256
	v_lshl_add_u64 v[86:87], v[86:87], 0, s[6:7]
	global_store_dwordx4 v[86:87], v[128:131], off offset:256
	v_lshl_add_u64 v[86:87], v[86:87], 0, s[6:7]
	s_waitcnt vmcnt(40)
	v_cvt_pk_bf16_f32 v68, v4, v5
	v_cvt_pk_bf16_f32 v69, v6, v7
	v_cvt_pk_bf16_f32 v70, v8, v9
	v_cvt_pk_bf16_f32 v71, v10, v11
	v_cvt_pk_bf16_f32 v72, v12, v13
	v_cvt_pk_bf16_f32 v73, v14, v15
	v_cvt_pk_bf16_f32 v74, v16, v17
	v_cvt_pk_bf16_f32 v75, v18, v19
	v_cvt_pk_bf16_f32 v76, v20, v21
	v_cvt_pk_bf16_f32 v77, v22, v23
	v_cvt_pk_bf16_f32 v78, v24, v25
	v_cvt_pk_bf16_f32 v79, v26, v27
	v_cvt_pk_bf16_f32 v80, v28, v29
	v_cvt_pk_bf16_f32 v81, v30, v31
	v_cvt_pk_bf16_f32 v82, v32, v33
	v_cvt_pk_bf16_f32 v83, v34, v35
	ds_write_b128 v2, v[68:71] offset:0
	ds_write_b128 v2, v[72:75] offset:16
	ds_write_b128 v2, v[76:79] offset:32
	ds_write_b128 v2, v[80:83] offset:48
	s_waitcnt vmcnt(8)
	v_cvt_pk_bf16_f32 v100, v36, v37
	v_cvt_pk_bf16_f32 v101, v38, v39
	v_cvt_pk_bf16_f32 v102, v40, v41
	v_cvt_pk_bf16_f32 v103, v42, v43
	v_cvt_pk_bf16_f32 v104, v44, v45
	v_cvt_pk_bf16_f32 v105, v46, v47
	v_cvt_pk_bf16_f32 v106, v48, v49
	v_cvt_pk_bf16_f32 v107, v50, v51
	v_cvt_pk_bf16_f32 v108, v52, v53
	v_cvt_pk_bf16_f32 v109, v54, v55
	v_cvt_pk_bf16_f32 v110, v56, v57
	v_cvt_pk_bf16_f32 v111, v58, v59
	v_cvt_pk_bf16_f32 v112, v60, v61
	v_cvt_pk_bf16_f32 v113, v62, v63
	v_cvt_pk_bf16_f32 v114, v64, v65
	v_cvt_pk_bf16_f32 v115, v66, v67
	ds_write_b128 v2, v[100:103] offset:64
	ds_write_b128 v2, v[104:107] offset:80
	ds_write_b128 v2, v[108:111] offset:96
	ds_write_b128 v2, v[112:115] offset:112
	v_mov_b32_e32 v86, v84
	v_mov_b32_e32 v87, v85
	ds_read_b128 v[116:119], v3 offset:0
	ds_read_b128 v[120:123], v3 offset:1152
	ds_read_b128 v[124:127], v3 offset:2304
	ds_read_b128 v[128:131], v3 offset:3456
	s_waitcnt lgkmcnt(0)
	global_store_dwordx4 v[86:87], v[116:119], off offset:384
	v_lshl_add_u64 v[86:87], v[86:87], 0, s[6:7]
	global_store_dwordx4 v[86:87], v[120:123], off offset:384
	v_lshl_add_u64 v[86:87], v[86:87], 0, s[6:7]
	global_store_dwordx4 v[86:87], v[124:127], off offset:384
	v_lshl_add_u64 v[86:87], v[86:87], 0, s[6:7]
	global_store_dwordx4 v[86:87], v[128:131], off offset:384
	v_lshl_add_u64 v[86:87], v[86:87], 0, s[6:7]
	ds_read_b128 v[116:119], v3 offset:4608
	ds_read_b128 v[120:123], v3 offset:5760
	ds_read_b128 v[124:127], v3 offset:6912
	ds_read_b128 v[128:131], v3 offset:8064
	s_waitcnt lgkmcnt(0)
	global_store_dwordx4 v[86:87], v[116:119], off offset:384
	v_lshl_add_u64 v[86:87], v[86:87], 0, s[6:7]
	global_store_dwordx4 v[86:87], v[120:123], off offset:384
	v_lshl_add_u64 v[86:87], v[86:87], 0, s[6:7]
	global_store_dwordx4 v[86:87], v[124:127], off offset:384
	v_lshl_add_u64 v[86:87], v[86:87], 0, s[6:7]
	global_store_dwordx4 v[86:87], v[128:131], off offset:384
	v_lshl_add_u64 v[86:87], v[86:87], 0, s[6:7]

; __device__ __forceinline__ void convert_item(const float* __restrict__ src, int Ksz, int Nsz, u16* __restrict__ dst, int kb, int nb,
;                                              int mode, const int tid) {
;   const int n = nb * NTHR + tid;
;   if (n < Nsz) {
;     const float* sp = src + (size_t)(kb * 64) * Nsz + n;
;     float v[64];
; #pragma unroll
;     for (int j = 0; j < 64; ++j) v[j] = sp[(size_t)j * Nsz];
;     int nd = n;
;     if (mode == 1) {
;       int isg = n >= 1024, c = n & 1023;
;       nd = (c >> 7) * 256 + isg * 128 + (c & 127);
;     }
;     u32x4* d = reinterpret_cast<u32x4*>(dst + (size_t)nd * Ksz + kb * 64);
; #pragma unroll
;     for (int q = 0; q < 8; ++q) {
;       u32x4 o;
;       o.x = pack2(v[q * 8 + 0], v[q * 8 + 1]);
;       o.y = pack2(v[q * 8 + 2], v[q * 8 + 3]);
;       o.z = pack2(v[q * 8 + 4], v[q * 8 + 5]);
;       o.w = pack2(v[q * 8 + 6], v[q * 8 + 7]);
;       d[q] = o;
;     }
;   }
; }
.Lcvp_nd:
	s_lshl_b32 s74, s69, 1
	s_lshl_b32 s75, s73, 1
	s_add_u32 s66, s66, s75
	s_addc_u32 s67, s67, 0
	s_lshl_b32 s6, s74, 3
	s_mov_b32 s7, 0
	v_mov_b32_e32 v86, s66
	v_mov_b32_e32 v87, s67
	v_mov_b32_e32 v88, s74
	v_mad_u64_u32 v[90:91], vcc, v84, v88, v[86:87]
	v_and_b32_e32 v0, 7, v130
	v_lshlrev_b32_e32 v0, 4, v0
	v_add_co_u32_e32 v84, vcc, v90, v0
	s_nop 1
	v_addc_co_u32_e32 v85, vcc, 0, v91, vcc
	v_lshlrev_b32_e32 v1, 2, v130
	v_lshrrev_b32_e32 v2, 6, v130
	v_mul_u32_u24_e32 v2, 0x2400, v2
	v_and_b32_e32 v3, 63, v130
	v_lshrrev_b32_e32 v89, 3, v3
	v_mul_u32_u24_e32 v89, 0x90, v89
	v_add3_u32 v89, v89, v0, v2
	v_mul_u32_u24_e32 v3, 0x90, v3
	v_add3_u32 v2, v2, v3, 32
	v_add_u32_e32 v3, 32, v89
	global_load_dword v4, v1, s[8:9] nt
	s_add_u32 s8, s8, s10
	s_addc_u32 s9, s9, 0
	global_load_dword v5, v1, s[8:9] nt
	s_add_u32 s8, s8, s10
	s_addc_u32 s9, s9, 0
	global_load_dword v6, v1, s[8:9] nt
	s_add_u32 s8, s8, s10
	s_addc_u32 s9, s9, 0
	global_load_dword v7, v1, s[8:9] nt
	s_add_u32 s8, s8, s10
	s_addc_u32 s9, s9, 0
	global_load_dword v8, v1, s[8:9] nt
	s_add_u32 s8, s8, s10
	s_addc_u32 s9, s9, 0
	global_load_dword v9, v1, s[8:9] nt
	s_add_u32 s8, s8, s10
	s_addc_u32 s9, s9, 0
	global_load_dword v10, v1, s[8:9] nt
	s_add_u32 s8, s8, s10
	s_addc_u32 s9, s9, 0
	global_load_dword v11, v1, s[8:9] nt
	s_add_u32 s8, s8, s10
	s_addc_u32 s9, s9, 0
	global_load_dword v12, v1, s[8:9] nt
	s_add_u32 s8, s8, s10
	s_addc_u32 s9, s9, 0
	global_load_dword v13, v1, s[8:9] nt
	s_add_u32 s8, s8, s10
	s_addc_u32 s9, s9, 0
	global_load_dword v14, v1, s[8:9] nt
	s_add_u32 s8, s8, s10
	s_addc_u32 s9, s9, 0
	global_load_dword v15, v1, s[8:9] nt
	s_add_u32 s8, s8, s10
	s_addc_u32 s9, s9, 0
	global_load_dword v16, v1, s[8:9] nt
	s_add_u32 s8, s8, s10
	s_addc_u32 s9, s9, 0
	global_load_dword v17, v1, s[8:9] nt
	s_add_u32 s8, s8, s10
	s_addc_u32 s9, s9, 0
	global_load_dword v18, v1, s[8:9] nt
	s_add_u32 s8, s8, s10
	s_addc_u32 s9, s9, 0
	global_load_dword v19, v1, s[8:9] nt
	s_add_u32 s8, s8, s10
	s_addc_u32 s9, s9, 0
	global_load_dword v20, v1, s[8:9] nt
	s_add_u32 s8, s8, s10
	s_addc_u32 s9, s9, 0
	global_load_dword v21, v1, s[8:9] nt
	s_add_u32 s8, s8, s10
	s_addc_u32 s9, s9, 0
	global_load_dword v22, v1, s[8:9] nt
	s_add_u32 s8, s8, s10
	s_addc_u32 s9, s9, 0
	global_load_dword v23, v1, s[8:9] nt
	s_add_u32 s8, s8, s10
	s_addc_u32 s9, s9, 0
	global_load_dword v24, v1, s[8:9] nt
	s_add_u32 s8, s8, s10
	s_addc_u32 s9, s9, 0
	global_load_dword v25, v1, s[8:9] nt
	s_add_u32 s8, s8, s10
	s_addc_u32 s9, s9, 0
	global_load_dword v26, v1, s[8:9] nt
	s_add_u32 s8, s8, s10
	s_addc_u32 s9, s9, 0
	global_load_dword v27, v1, s[8:9] nt
	s_add_u32 s8, s8, s10
	s_addc_u32 s9, s9, 0
	global_load_dword v28, v1, s[8:9] nt
	s_add_u32 s8, s8, s10
	s_addc_u32 s9, s9, 0
	global_load_dword v29, v1, s[8:9] nt
	s_add_u32 s8, s8, s10
	s_addc_u32 s9, s9, 0
	global_load_dword v30, v1, s[8:9] nt
	s_add_u32 s8, s8, s10
	s_addc_u32 s9, s9, 0
	global_load_dword v31, v1, s[8:9] nt
	s_add_u32 s8, s8, s10
	s_addc_u32 s9, s9, 0
	global_load_dword v32, v1, s[8:9] nt
	s_add_u32 s8, s8, s10
	s_addc_u32 s9, s9, 0
	global_load_dword v33, v1, s[8:9] nt
	s_add_u32 s8, s8, s10
	s_addc_u32 s9, s9, 0
	global_load_dword v34, v1, s[8:9] nt
	s_add_u32 s8, s8, s10
	s_addc_u32 s9, s9, 0
	global_load_dword v35, v1, s[8:9] nt
	s_add_u32 s8, s8, s10
	s_addc_u32 s9, s9, 0
	global_load_dword v36, v1, s[8:9] nt
	s_add_u32 s8, s8, s10
	s_addc_u32 s9, s9, 0
	global_load_dword v37, v1, s[8:9] nt
	s_add_u32 s8, s8, s10
	s_addc_u32 s9, s9, 0
	global_load_dword v38, v1, s[8:9] nt
	s_add_u32 s8, s8, s10
	s_addc_u32 s9, s9, 0
	global_load_dword v39, v1, s[8:9] nt
	s_add_u32 s8, s8, s10
	s_addc_u32 s9, s9, 0
	global_load_dword v40, v1, s[8:9] nt
	s_add_u32 s8, s8, s10
	s_addc_u32 s9, s9, 0
	global_load_dword v41, v1, s[8:9] nt
	s_add_u32 s8, s8, s10
	s_addc_u32 s9, s9, 0
	global_load_dword v42, v1, s[8:9] nt
	s_add_u32 s8, s8, s10
	s_addc_u32 s9, s9, 0
	global_load_dword v43, v1, s[8:9] nt
	s_add_u32 s8, s8, s10
	s_addc_u32 s9, s9, 0
	global_load_dword v44, v1, s[8:9] nt
	s_add_u32 s8, s8, s10
	s_addc_u32 s9, s9, 0
	global_load_dword v45, v1, s[8:9] nt
	s_add_u32 s8, s8, s10
	s_addc_u32 s9, s9, 0
	global_load_dword v46, v1, s[8:9] nt
	s_add_u32 s8, s8, s10
	s_addc_u32 s9, s9, 0
	global_load_dword v47, v1, s[8:9] nt
	s_add_u32 s8, s8, s10
	s_addc_u32 s9, s9, 0
	global_load_dword v48, v1, s[8:9] nt
	s_add_u32 s8, s8, s10
	s_addc_u32 s9, s9, 0
	global_load_dword v49, v1, s[8:9] nt
	s_add_u32 s8, s8, s10
	s_addc_u32 s9, s9, 0
	global_load_dword v50, v1, s[8:9] nt
	s_add_u32 s8, s8, s10
	s_addc_u32 s9, s9, 0
	global_load_dword v51, v1, s[8:9] nt
	s_add_u32 s8, s8, s10
	s_addc_u32 s9, s9, 0
	global_load_dword v52, v1, s[8:9] nt
	s_add_u32 s8, s8, s10
	s_addc_u32 s9, s9, 0
	global_load_dword v53, v1, s[8:9] nt
	s_add_u32 s8, s8, s10
	s_addc_u32 s9, s9, 0
	global_load_dword v54, v1, s[8:9] nt
	s_add_u32 s8, s8, s10
	s_addc_u32 s9, s9, 0
	global_load_dword v55, v1, s[8:9] nt
	s_add_u32 s8, s8, s10
	s_addc_u32 s9, s9, 0
	global_load_dword v56, v1, s[8:9] nt
	s_add_u32 s8, s8, s10
	s_addc_u32 s9, s9, 0
	global_load_dword v57, v1, s[8:9] nt
	s_add_u32 s8, s8, s10
	s_addc_u32 s9, s9, 0
	global_load_dword v58, v1, s[8:9] nt
	s_add_u32 s8, s8, s10
	s_addc_u32 s9, s9, 0
	global_load_dword v59, v1, s[8:9] nt
	s_add_u32 s8, s8, s10
	s_addc_u32 s9, s9, 0
	global_load_dword v60, v1, s[8:9] nt
	s_add_u32 s8, s8, s10
	s_addc_u32 s9, s9, 0
	global_load_dword v61, v1, s[8:9] nt
	s_add_u32 s8, s8, s10
	s_addc_u32 s9, s9, 0
	global_load_dword v62, v1, s[8:9] nt
	s_add_u32 s8, s8, s10
	s_addc_u32 s9, s9, 0
	global_load_dword v63, v1, s[8:9] nt
	s_add_u32 s8, s8, s10
	s_addc_u32 s9, s9, 0
	global_load_dword v64, v1, s[8:9] nt
	s_add_u32 s8, s8, s10
	s_addc_u32 s9, s9, 0
	global_load_dword v65, v1, s[8:9] nt
	s_add_u32 s8, s8, s10
	s_addc_u32 s9, s9, 0
	global_load_dword v66, v1, s[8:9] nt
	s_add_u32 s8, s8, s10
	s_addc_u32 s9, s9, 0
	global_load_dword v67, v1, s[8:9] nt
	s_add_u32 s8, s8, s10
	s_addc_u32 s9, s9, 0
	s_waitcnt vmcnt(32)
; __device__ __forceinline__ void convert_item(const float* __restrict__ src, int Ksz, int Nsz, u16* __restrict__ dst, int kb, int nb,
;                                              int mode, const int tid) {
;     ...
; #pragma unroll
;     for (int j = 0; j < 64; ++j) v[j] = sp[(size_t)j * Nsz];
;     int nd = n;
;     if (mode == 1) {
;       int isg = n >= 1024, c = n & 1023;
;       nd = (c >> 7) * 256 + isg * 128 + (c & 127);
;     }
;     u32x4* d = reinterpret_cast<u32x4*>(dst + (size_t)nd * Ksz + kb * 64);
; #pragma unroll
;     for (int q = 0; q < 8; ++q) {
;       u32x4 o;
;       o.x = pack2(v[q * 8 + 0], v[q * 8 + 1]);
;       o.y = pack2(v[q * 8 + 2], v[q * 8 + 3]);
;       o.z = pack2(v[q * 8 + 4], v[q * 8 + 5]);
;       o.w = pack2(v[q * 8 + 6], v[q * 8 + 7]);
;       d[q] = o;
;     }
	v_cvt_pk_bf16_f32 v68, v4, v5
	v_cvt_pk_bf16_f32 v69, v6, v7
	v_cvt_pk_bf16_f32 v70, v8, v9
	v_cvt_pk_bf16_f32 v71, v10, v11
	v_cvt_pk_bf16_f32 v72, v12, v13
	v_cvt_pk_bf16_f32 v73, v14, v15
	v_cvt_pk_bf16_f32 v74, v16, v17
	v_cvt_pk_bf16_f32 v75, v18, v19
	v_cvt_pk_bf16_f32 v76, v20, v21
	v_cvt_pk_bf16_f32 v77, v22, v23
	v_cvt_pk_bf16_f32 v78, v24, v25
	v_cvt_pk_bf16_f32 v79, v26, v27
	v_cvt_pk_bf16_f32 v80, v28, v29
	v_cvt_pk_bf16_f32 v81, v30, v31
	v_cvt_pk_bf16_f32 v82, v32, v33
	v_cvt_pk_bf16_f32 v83, v34, v35
	ds_write_b128 v2, v[68:71] offset:0
	ds_write_b128 v2, v[72:75] offset:16
	ds_write_b128 v2, v[76:79] offset:32
	ds_write_b128 v2, v[80:83] offset:48
	global_load_dword v4, v1, s[8:9] nt
	s_add_u32 s8, s8, s10
	s_addc_u32 s9, s9, 0
	global_load_dword v5, v1, s[8:9] nt
	s_add_u32 s8, s8, s10
	s_addc_u32 s9, s9, 0
	global_load_dword v6, v1, s[8:9] nt
	s_add_u32 s8, s8, s10
	s_addc_u32 s9, s9, 0
	global_load_dword v7, v1, s[8:9] nt
	s_add_u32 s8, s8, s10
	s_addc_u32 s9, s9, 0
	global_load_dword v8, v1, s[8:9] nt
	s_add_u32 s8, s8, s10
	s_addc_u32 s9, s9, 0
	global_load_dword v9, v1, s[8:9] nt
	s_add_u32 s8, s8, s10
	s_addc_u32 s9, s9, 0
	global_load_dword v10, v1, s[8:9] nt
	s_add_u32 s8, s8, s10
	s_addc_u32 s9, s9, 0
	global_load_dword v11, v1, s[8:9] nt
	s_add_u32 s8, s8, s10
	s_addc_u32 s9, s9, 0
	global_load_dword v12, v1, s[8:9] nt
	s_add_u32 s8, s8, s10
	s_addc_u32 s9, s9, 0
	global_load_dword v13, v1, s[8:9] nt
	s_add_u32 s8, s8, s10
	s_addc_u32 s9, s9, 0
	global_load_dword v14, v1, s[8:9] nt
	s_add_u32 s8, s8, s10
	s_addc_u32 s9, s9, 0
	global_load_dword v15, v1, s[8:9] nt
	s_add_u32 s8, s8, s10
	s_addc_u32 s9, s9, 0
	global_load_dword v16, v1, s[8:9] nt
	s_add_u32 s8, s8, s10
	s_addc_u32 s9, s9, 0
	global_load_dword v17, v1, s[8:9] nt
	s_add_u32 s8, s8, s10
	s_addc_u32 s9, s9, 0
	global_load_dword v18, v1, s[8:9] nt
	s_add_u32 s8, s8, s10
	s_addc_u32 s9, s9, 0
	global_load_dword v19, v1, s[8:9] nt
	s_add_u32 s8, s8, s10
	s_addc_u32 s9, s9, 0
	global_load_dword v20, v1, s[8:9] nt
	s_add_u32 s8, s8, s10
	s_addc_u32 s9, s9, 0
	global_load_dword v21, v1, s[8:9] nt
	s_add_u32 s8, s8, s10
	s_addc_u32 s9, s9, 0
	global_load_dword v22, v1, s[8:9] nt
	s_add_u32 s8, s8, s10
	s_addc_u32 s9, s9, 0
	global_load_dword v23, v1, s[8:9] nt
	s_add_u32 s8, s8, s10
	s_addc_u32 s9, s9, 0
	global_load_dword v24, v1, s[8:9] nt
	s_add_u32 s8, s8, s10
	s_addc_u32 s9, s9, 0
	global_load_dword v25, v1, s[8:9] nt
	s_add_u32 s8, s8, s10
	s_addc_u32 s9, s9, 0
	global_load_dword v26, v1, s[8:9] nt
	s_add_u32 s8, s8, s10
	s_addc_u32 s9, s9, 0
	global_load_dword v27, v1, s[8:9] nt
	s_add_u32 s8, s8, s10
	s_addc_u32 s9, s9, 0
	global_load_dword v28, v1, s[8:9] nt
	s_add_u32 s8, s8, s10
	s_addc_u32 s9, s9, 0
	global_load_dword v29, v1, s[8:9] nt
	s_add_u32 s8, s8, s10
	s_addc_u32 s9, s9, 0
	global_load_dword v30, v1, s[8:9] nt
	s_add_u32 s8, s8, s10
	s_addc_u32 s9, s9, 0
	global_load_dword v31, v1, s[8:9] nt
	s_add_u32 s8, s8, s10
	s_addc_u32 s9, s9, 0
	global_load_dword v32, v1, s[8:9] nt
	s_add_u32 s8, s8, s10
	s_addc_u32 s9, s9, 0
	global_load_dword v33, v1, s[8:9] nt
	s_add_u32 s8, s8, s10
	s_addc_u32 s9, s9, 0
	global_load_dword v34, v1, s[8:9] nt
	s_add_u32 s8, s8, s10
	s_addc_u32 s9, s9, 0
	global_load_dword v35, v1, s[8:9] nt
	s_add_u32 s8, s8, s10
	s_addc_u32 s9, s9, 0
	s_waitcnt vmcnt(32)
	v_cvt_pk_bf16_f32 v100, v36, v37
	v_cvt_pk_bf16_f32 v101, v38, v39
	v_cvt_pk_bf16_f32 v102, v40, v41
	v_cvt_pk_bf16_f32 v103, v42, v43
	v_cvt_pk_bf16_f32 v104, v44, v45
	v_cvt_pk_bf16_f32 v105, v46, v47
	v_cvt_pk_bf16_f32 v106, v48, v49
	v_cvt_pk_bf16_f32 v107, v50, v51
	v_cvt_pk_bf16_f32 v108, v52, v53
	v_cvt_pk_bf16_f32 v109, v54, v55
	v_cvt_pk_bf16_f32 v110, v56, v57
	v_cvt_pk_bf16_f32 v111, v58, v59
	v_cvt_pk_bf16_f32 v112, v60, v61
	v_cvt_pk_bf16_f32 v113, v62, v63
	v_cvt_pk_bf16_f32 v114, v64, v65
	v_cvt_pk_bf16_f32 v115, v66, v67
	ds_write_b128 v2, v[100:103] offset:64
	ds_write_b128 v2, v[104:107] offset:80
	ds_write_b128 v2, v[108:111] offset:96
	ds_write_b128 v2, v[112:115] offset:112
	global_load_dword v36, v1, s[8:9] nt
	s_add_u32 s8, s8, s10
	s_addc_u32 s9, s9, 0
	global_load_dword v37, v1, s[8:9] nt
	s_add_u32 s8, s8, s10
	s_addc_u32 s9, s9, 0
	global_load_dword v38, v1, s[8:9] nt
	s_add_u32 s8, s8, s10
	s_addc_u32 s9, s9, 0
	global_load_dword v39, v1, s[8:9] nt
	s_add_u32 s8, s8, s10
	s_addc_u32 s9, s9, 0
	global_load_dword v40, v1, s[8:9] nt
	s_add_u32 s8, s8, s10
	s_addc_u32 s9, s9, 0
	global_load_dword v41, v1, s[8:9] nt
	s_add_u32 s8, s8, s10
	s_addc_u32 s9, s9, 0
	global_load_dword v42, v1, s[8:9] nt
	s_add_u32 s8, s8, s10
	s_addc_u32 s9, s9, 0
	global_load_dword v43, v1, s[8:9] nt
	s_add_u32 s8, s8, s10
	s_addc_u32 s9, s9, 0
	global_load_dword v44, v1, s[8:9] nt
	s_add_u32 s8, s8, s10
	s_addc_u32 s9, s9, 0
	global_load_dword v45, v1, s[8:9] nt
	s_add_u32 s8, s8, s10
	s_addc_u32 s9, s9, 0
	global_load_dword v46, v1, s[8:9] nt
	s_add_u32 s8, s8, s10
	s_addc_u32 s9, s9, 0
	global_load_dword v47, v1, s[8:9] nt
	s_add_u32 s8, s8, s10
	s_addc_u32 s9, s9, 0
	global_load_dword v48, v1, s[8:9] nt
	s_add_u32 s8, s8, s10
	s_addc_u32 s9, s9, 0
	global_load_dword v49, v1, s[8:9] nt
	s_add_u32 s8, s8, s10
	s_addc_u32 s9, s9, 0
	global_load_dword v50, v1, s[8:9] nt
	s_add_u32 s8, s8, s10
	s_addc_u32 s9, s9, 0
	global_load_dword v51, v1, s[8:9] nt
	s_add_u32 s8, s8, s10
	s_addc_u32 s9, s9, 0
	global_load_dword v52, v1, s[8:9] nt
	s_add_u32 s8, s8, s10
	s_addc_u32 s9, s9, 0
	global_load_dword v53, v1, s[8:9] nt
	s_add_u32 s8, s8, s10
	s_addc_u32 s9, s9, 0
	global_load_dword v54, v1, s[8:9] nt
	s_add_u32 s8, s8, s10
	s_addc_u32 s9, s9, 0
	global_load_dword v55, v1, s[8:9] nt
	s_add_u32 s8, s8, s10
	s_addc_u32 s9, s9, 0
	global_load_dword v56, v1, s[8:9] nt
	s_add_u32 s8, s8, s10
	s_addc_u32 s9, s9, 0
	global_load_dword v57, v1, s[8:9] nt
	s_add_u32 s8, s8, s10
	s_addc_u32 s9, s9, 0
	global_load_dword v58, v1, s[8:9] nt
	s_add_u32 s8, s8, s10
	s_addc_u32 s9, s9, 0
	global_load_dword v59, v1, s[8:9] nt
	s_add_u32 s8, s8, s10
	s_addc_u32 s9, s9, 0
	global_load_dword v60, v1, s[8:9] nt
	s_add_u32 s8, s8, s10
	s_addc_u32 s9, s9, 0
	global_load_dword v61, v1, s[8:9] nt
	s_add_u32 s8, s8, s10
	s_addc_u32 s9, s9, 0
	global_load_dword v62, v1, s[8:9] nt
	s_add_u32 s8, s8, s10
	s_addc_u32 s9, s9, 0
	global_load_dword v63, v1, s[8:9] nt
	s_add_u32 s8, s8, s10
	s_addc_u32 s9, s9, 0
	global_load_dword v64, v1, s[8:9] nt
	s_add_u32 s8, s8, s10
	s_addc_u32 s9, s9, 0
	global_load_dword v65, v1, s[8:9] nt
	s_add_u32 s8, s8, s10
	s_addc_u32 s9, s9, 0
	global_load_dword v66, v1, s[8:9] nt
	s_add_u32 s8, s8, s10
	s_addc_u32 s9, s9, 0
	global_load_dword v67, v1, s[8:9] nt
	s_add_u32 s8, s8, s10
	s_addc_u32 s9, s9, 0
	v_mov_b32_e32 v86, v84
	v_mov_b32_e32 v87, v85
	ds_read_b128 v[116:119], v3 offset:0
	ds_read_b128 v[120:123], v3 offset:1152
	ds_read_b128 v[124:127], v3 offset:2304
	ds_read_b128 v[128:131], v3 offset:3456
	s_waitcnt lgkmcnt(0)
; __device__ __forceinline__ void convert_item(const float* __restrict__ src, int Ksz, int Nsz, u16* __restrict__ dst, int kb, int nb,
;                                              int mode, const int tid) {
;     ...
; #pragma unroll
;     for (int j = 0; j < 64; ++j) v[j] = sp[(size_t)j * Nsz];
;     int nd = n;
;     if (mode == 1) {
;       int isg = n >= 1024, c = n & 1023;
;       nd = (c >> 7) * 256 + isg * 128 + (c & 127);
;     }
;     u32x4* d = reinterpret_cast<u32x4*>(dst + (size_t)nd * Ksz + kb * 64);
; #pragma unroll
;     for (int q = 0; q < 8; ++q) {
;       u32x4 o;
;       o.x = pack2(v[q * 8 + 0], v[q * 8 + 1]);
;       o.y = pack2(v[q * 8 + 2], v[q * 8 + 3]);
;       o.z = pack2(v[q * 8 + 4], v[q * 8 + 5]);
;       o.w = pack2(v[q * 8 + 6], v[q * 8 + 7]);
;       d[q] = o;
;     }
	global_store_dwordx4 v[86:87], v[116:119], off offset:0
	v_lshl_add_u64 v[86:87], v[86:87], 0, s[6:7]
	global_store_dwordx4 v[86:87], v[120:123], off offset:0
	v_lshl_add_u64 v[86:87], v[86:87], 0, s[6:7]
	global_store_dwordx4 v[86:87], v[124:127], off offset:0
	v_lshl_add_u64 v[86:87], v[86:87], 0, s[6:7]
	global_store_dwordx4 v[86:87], v[128:131], off offset:0
	v_lshl_add_u64 v[86:87], v[86:87], 0, s[6:7]
	ds_read_b128 v[116:119], v3 offset:4608
	ds_read_b128 v[120:123], v3 offset:5760
	ds_read_b128 v[124:127], v3 offset:6912
	ds_read_b128 v[128:131], v3 offset:8064
	s_waitcnt lgkmcnt(0)
	global_store_dwordx4 v[86:87], v[116:119], off offset:0
	v_lshl_add_u64 v[86:87], v[86:87], 0, s[6:7]
	global_store_dwordx4 v[86:87], v[120:123], off offset:0
	v_lshl_add_u64 v[86:87], v[86:87], 0, s[6:7]
	global_store_dwordx4 v[86:87], v[124:127], off offset:0
	v_lshl_add_u64 v[86:87], v[86:87], 0, s[6:7]
	global_store_dwordx4 v[86:87], v[128:131], off offset:0
	v_lshl_add_u64 v[86:87], v[86:87], 0, s[6:7]
	s_waitcnt vmcnt(40)
	v_cvt_pk_bf16_f32 v68, v4, v5
	v_cvt_pk_bf16_f32 v69, v6, v7
	v_cvt_pk_bf16_f32 v70, v8, v9
	v_cvt_pk_bf16_f32 v71, v10, v11
	v_cvt_pk_bf16_f32 v72, v12, v13
	v_cvt_pk_bf16_f32 v73, v14, v15
	v_cvt_pk_bf16_f32 v74, v16, v17
	v_cvt_pk_bf16_f32 v75, v18, v19
	v_cvt_pk_bf16_f32 v76, v20, v21
	v_cvt_pk_bf16_f32 v77, v22, v23
	v_cvt_pk_bf16_f32 v78, v24, v25
	v_cvt_pk_bf16_f32 v79, v26, v27
	v_cvt_pk_bf16_f32 v80, v28, v29
	v_cvt_pk_bf16_f32 v81, v30, v31
	v_cvt_pk_bf16_f32 v82, v32, v33
	v_cvt_pk_bf16_f32 v83, v34, v35
	ds_write_b128 v2, v[68:71] offset:0
	ds_write_b128 v2, v[72:75] offset:16
	ds_write_b128 v2, v[76:79] offset:32
	ds_write_b128 v2, v[80:83] offset:48
	global_load_dword v4, v1, s[8:9] nt
	s_add_u32 s8, s8, s10
	s_addc_u32 s9, s9, 0
	global_load_dword v5, v1, s[8:9] nt
	s_add_u32 s8, s8, s10
	s_addc_u32 s9, s9, 0
	global_load_dword v6, v1, s[8:9] nt
	s_add_u32 s8, s8, s10
	s_addc_u32 s9, s9, 0
	global_load_dword v7, v1, s[8:9] nt
	s_add_u32 s8, s8, s10
	s_addc_u32 s9, s9, 0
	global_load_dword v8, v1, s[8:9] nt
	s_add_u32 s8, s8, s10
	s_addc_u32 s9, s9, 0
	global_load_dword v9, v1, s[8:9] nt
	s_add_u32 s8, s8, s10
	s_addc_u32 s9, s9, 0
	global_load_dword v10, v1, s[8:9] nt
	s_add_u32 s8, s8, s10
	s_addc_u32 s9, s9, 0
	global_load_dword v11, v1, s[8:9] nt
	s_add_u32 s8, s8, s10
	s_addc_u32 s9, s9, 0
	global_load_dword v12, v1, s[8:9] nt
	s_add_u32 s8, s8, s10
	s_addc_u32 s9, s9, 0
	global_load_dword v13, v1, s[8:9] nt
	s_add_u32 s8, s8, s10
	s_addc_u32 s9, s9, 0
	global_load_dword v14, v1, s[8:9] nt
	s_add_u32 s8, s8, s10
	s_addc_u32 s9, s9, 0
	global_load_dword v15, v1, s[8:9] nt
	s_add_u32 s8, s8, s10
	s_addc_u32 s9, s9, 0
	global_load_dword v16, v1, s[8:9] nt
	s_add_u32 s8, s8, s10
	s_addc_u32 s9, s9, 0
	global_load_dword v17, v1, s[8:9] nt
	s_add_u32 s8, s8, s10
	s_addc_u32 s9, s9, 0
	global_load_dword v18, v1, s[8:9] nt
	s_add_u32 s8, s8, s10
	s_addc_u32 s9, s9, 0
	global_load_dword v19, v1, s[8:9] nt
	s_add_u32 s8, s8, s10
	s_addc_u32 s9, s9, 0
	global_load_dword v20, v1, s[8:9] nt
	s_add_u32 s8, s8, s10
	s_addc_u32 s9, s9, 0
	global_load_dword v21, v1, s[8:9] nt
	s_add_u32 s8, s8, s10
	s_addc_u32 s9, s9, 0
	global_load_dword v22, v1, s[8:9] nt
	s_add_u32 s8, s8, s10
	s_addc_u32 s9, s9, 0
	global_load_dword v23, v1, s[8:9] nt
	s_add_u32 s8, s8, s10
	s_addc_u32 s9, s9, 0
	global_load_dword v24, v1, s[8:9] nt
	s_add_u32 s8, s8, s10
	s_addc_u32 s9, s9, 0
	global_load_dword v25, v1, s[8:9] nt
	s_add_u32 s8, s8, s10
	s_addc_u32 s9, s9, 0
	global_load_dword v26, v1, s[8:9] nt
	s_add_u32 s8, s8, s10
	s_addc_u32 s9, s9, 0
	global_load_dword v27, v1, s[8:9] nt
	s_add_u32 s8, s8, s10
	s_addc_u32 s9, s9, 0
	global_load_dword v28, v1, s[8:9] nt
	s_add_u32 s8, s8, s10
	s_addc_u32 s9, s9, 0
	global_load_dword v29, v1, s[8:9] nt
	s_add_u32 s8, s8, s10
	s_addc_u32 s9, s9, 0
	global_load_dword v30, v1, s[8:9] nt
	s_add_u32 s8, s8, s10
	s_addc_u32 s9, s9, 0
	global_load_dword v31, v1, s[8:9] nt
	s_add_u32 s8, s8, s10
	s_addc_u32 s9, s9, 0
	global_load_dword v32, v1, s[8:9] nt
	s_add_u32 s8, s8, s10
	s_addc_u32 s9, s9, 0
	global_load_dword v33, v1, s[8:9] nt
	s_add_u32 s8, s8, s10
	s_addc_u32 s9, s9, 0
	global_load_dword v34, v1, s[8:9] nt
	s_add_u32 s8, s8, s10
	s_addc_u32 s9, s9, 0
	global_load_dword v35, v1, s[8:9] nt
	s_add_u32 s8, s8, s10
	s_addc_u32 s9, s9, 0
	s_waitcnt vmcnt(40)
; __device__ __forceinline__ void convert_item(const float* __restrict__ src, int Ksz, int Nsz, u16* __restrict__ dst, int kb, int nb,
;                                              int mode, const int tid) {
;     ...
; #pragma unroll
;     for (int j = 0; j < 64; ++j) v[j] = sp[(size_t)j * Nsz];
;     int nd = n;
;     if (mode == 1) {
;       int isg = n >= 1024, c = n & 1023;
;       nd = (c >> 7) * 256 + isg * 128 + (c & 127);
;     }
;     u32x4* d = reinterpret_cast<u32x4*>(dst + (size_t)nd * Ksz + kb * 64);
; #pragma unroll
;     for (int q = 0; q < 8; ++q) {
;       u32x4 o;
;       o.x = pack2(v[q * 8 + 0], v[q * 8 + 1]);
;       o.y = pack2(v[q * 8 + 2], v[q * 8 + 3]);
;       o.z = pack2(v[q * 8 + 4], v[q * 8 + 5]);
;       o.w = pack2(v[q * 8 + 6], v[q * 8 + 7]);
;       d[q] = o;
;     }
	v_cvt_pk_bf16_f32 v100, v36, v37
	v_cvt_pk_bf16_f32 v101, v38, v39
	v_cvt_pk_bf16_f32 v102, v40, v41
	v_cvt_pk_bf16_f32 v103, v42, v43
	v_cvt_pk_bf16_f32 v104, v44, v45
	v_cvt_pk_bf16_f32 v105, v46, v47
	v_cvt_pk_bf16_f32 v106, v48, v49
	v_cvt_pk_bf16_f32 v107, v50, v51
	v_cvt_pk_bf16_f32 v108, v52, v53
	v_cvt_pk_bf16_f32 v109, v54, v55
	v_cvt_pk_bf16_f32 v110, v56, v57
	v_cvt_pk_bf16_f32 v111, v58, v59
	v_cvt_pk_bf16_f32 v112, v60, v61
	v_cvt_pk_bf16_f32 v113, v62, v63
	v_cvt_pk_bf16_f32 v114, v64, v65
	v_cvt_pk_bf16_f32 v115, v66, v67
	ds_write_b128 v2, v[100:103] offset:64
	ds_write_b128 v2, v[104:107] offset:80
	ds_write_b128 v2, v[108:111] offset:96
	ds_write_b128 v2, v[112:115] offset:112
	global_load_dword v36, v1, s[8:9] nt
	s_add_u32 s8, s8, s10
	s_addc_u32 s9, s9, 0
	global_load_dword v37, v1, s[8:9] nt
	s_add_u32 s8, s8, s10
	s_addc_u32 s9, s9, 0
	global_load_dword v38, v1, s[8:9] nt
	s_add_u32 s8, s8, s10
	s_addc_u32 s9, s9, 0
	global_load_dword v39, v1, s[8:9] nt
	s_add_u32 s8, s8, s10
	s_addc_u32 s9, s9, 0
	global_load_dword v40, v1, s[8:9] nt
	s_add_u32 s8, s8, s10
	s_addc_u32 s9, s9, 0
	global_load_dword v41, v1, s[8:9] nt
	s_add_u32 s8, s8, s10
	s_addc_u32 s9, s9, 0
	global_load_dword v42, v1, s[8:9] nt
	s_add_u32 s8, s8, s10
	s_addc_u32 s9, s9, 0
	global_load_dword v43, v1, s[8:9] nt
	s_add_u32 s8, s8, s10
	s_addc_u32 s9, s9, 0
	global_load_dword v44, v1, s[8:9] nt
	s_add_u32 s8, s8, s10
	s_addc_u32 s9, s9, 0
	global_load_dword v45, v1, s[8:9] nt
	s_add_u32 s8, s8, s10
	s_addc_u32 s9, s9, 0
	global_load_dword v46, v1, s[8:9] nt
	s_add_u32 s8, s8, s10
	s_addc_u32 s9, s9, 0
	global_load_dword v47, v1, s[8:9] nt
	s_add_u32 s8, s8, s10
	s_addc_u32 s9, s9, 0
	global_load_dword v48, v1, s[8:9] nt
	s_add_u32 s8, s8, s10
	s_addc_u32 s9, s9, 0
	global_load_dword v49, v1, s[8:9] nt
	s_add_u32 s8, s8, s10
	s_addc_u32 s9, s9, 0
	global_load_dword v50, v1, s[8:9] nt
	s_add_u32 s8, s8, s10
	s_addc_u32 s9, s9, 0
	global_load_dword v51, v1, s[8:9] nt
	s_add_u32 s8, s8, s10
	s_addc_u32 s9, s9, 0
	global_load_dword v52, v1, s[8:9] nt
	s_add_u32 s8, s8, s10
	s_addc_u32 s9, s9, 0
	global_load_dword v53, v1, s[8:9] nt
	s_add_u32 s8, s8, s10
	s_addc_u32 s9, s9, 0
	global_load_dword v54, v1, s[8:9] nt
	s_add_u32 s8, s8, s10
	s_addc_u32 s9, s9, 0
	global_load_dword v55, v1, s[8:9] nt
	s_add_u32 s8, s8, s10
	s_addc_u32 s9, s9, 0
	global_load_dword v56, v1, s[8:9] nt
	s_add_u32 s8, s8, s10
	s_addc_u32 s9, s9, 0
	global_load_dword v57, v1, s[8:9] nt
	s_add_u32 s8, s8, s10
	s_addc_u32 s9, s9, 0
	global_load_dword v58, v1, s[8:9] nt
	s_add_u32 s8, s8, s10
	s_addc_u32 s9, s9, 0
	global_load_dword v59, v1, s[8:9] nt
	s_add_u32 s8, s8, s10
	s_addc_u32 s9, s9, 0
	global_load_dword v60, v1, s[8:9] nt
	s_add_u32 s8, s8, s10
	s_addc_u32 s9, s9, 0
	global_load_dword v61, v1, s[8:9] nt
	s_add_u32 s8, s8, s10
	s_addc_u32 s9, s9, 0
	global_load_dword v62, v1, s[8:9] nt
	s_add_u32 s8, s8, s10
	s_addc_u32 s9, s9, 0
	global_load_dword v63, v1, s[8:9] nt
	s_add_u32 s8, s8, s10
	s_addc_u32 s9, s9, 0
	global_load_dword v64, v1, s[8:9] nt
	s_add_u32 s8, s8, s10
	s_addc_u32 s9, s9, 0
	global_load_dword v65, v1, s[8:9] nt
	s_add_u32 s8, s8, s10
	s_addc_u32 s9, s9, 0
	global_load_dword v66, v1, s[8:9] nt
	s_add_u32 s8, s8, s10
	s_addc_u32 s9, s9, 0
	global_load_dword v67, v1, s[8:9] nt
	s_add_u32 s8, s8, s10
	s_addc_u32 s9, s9, 0
	v_mov_b32_e32 v86, v84
	v_mov_b32_e32 v87, v85
	ds_read_b128 v[116:119], v3 offset:0
	ds_read_b128 v[120:123], v3 offset:1152
	ds_read_b128 v[124:127], v3 offset:2304
	ds_read_b128 v[128:131], v3 offset:3456
	s_waitcnt lgkmcnt(0)
	global_store_dwordx4 v[86:87], v[116:119], off offset:128
	v_lshl_add_u64 v[86:87], v[86:87], 0, s[6:7]
	global_store_dwordx4 v[86:87], v[120:123], off offset:128
	v_lshl_add_u64 v[86:87], v[86:87], 0, s[6:7]
	global_store_dwordx4 v[86:87], v[124:127], off offset:128
	v_lshl_add_u64 v[86:87], v[86:87], 0, s[6:7]
	global_store_dwordx4 v[86:87], v[128:131], off offset:128
	v_lshl_add_u64 v[86:87], v[86:87], 0, s[6:7]
	ds_read_b128 v[116:119], v3 offset:4608
	ds_read_b128 v[120:123], v3 offset:5760
	ds_read_b128 v[124:127], v3 offset:6912
	ds_read_b128 v[128:131], v3 offset:8064
	s_waitcnt lgkmcnt(0)
	global_store_dwordx4 v[86:87], v[116:119], off offset:128
	v_lshl_add_u64 v[86:87], v[86:87], 0, s[6:7]
	global_store_dwordx4 v[86:87], v[120:123], off offset:128
	v_lshl_add_u64 v[86:87], v[86:87], 0, s[6:7]
	global_store_dwordx4 v[86:87], v[124:127], off offset:128
	v_lshl_add_u64 v[86:87], v[86:87], 0, s[6:7]
	global_store_dwordx4 v[86:87], v[128:131], off offset:128
	v_lshl_add_u64 v[86:87], v[86:87], 0, s[6:7]
	s_waitcnt vmcnt(40)
; __device__ __forceinline__ void convert_item(const float* __restrict__ src, int Ksz, int Nsz, u16* __restrict__ dst, int kb, int nb,
;                                              int mode, const int tid) {
;     ...
; #pragma unroll
;     for (int j = 0; j < 64; ++j) v[j] = sp[(size_t)j * Nsz];
;     int nd = n;
;     if (mode == 1) {
;       int isg = n >= 1024, c = n & 1023;
;       nd = (c >> 7) * 256 + isg * 128 + (c & 127);
;     }
;     u32x4* d = reinterpret_cast<u32x4*>(dst + (size_t)nd * Ksz + kb * 64);
; #pragma unroll
;     for (int q = 0; q < 8; ++q) {
;       u32x4 o;
;       o.x = pack2(v[q * 8 + 0], v[q * 8 + 1]);
;       o.y = pack2(v[q * 8 + 2], v[q * 8 + 3]);
;       o.z = pack2(v[q * 8 + 4], v[q * 8 + 5]);
;       o.w = pack2(v[q * 8 + 6], v[q * 8 + 7]);
;       d[q] = o;
;     }
	v_cvt_pk_bf16_f32 v68, v4, v5
	v_cvt_pk_bf16_f32 v69, v6, v7
	v_cvt_pk_bf16_f32 v70, v8, v9
	v_cvt_pk_bf16_f32 v71, v10, v11
	v_cvt_pk_bf16_f32 v72, v12, v13
	v_cvt_pk_bf16_f32 v73, v14, v15
	v_cvt_pk_bf16_f32 v74, v16, v17
	v_cvt_pk_bf16_f32 v75, v18, v19
	v_cvt_pk_bf16_f32 v76, v20, v21
	v_cvt_pk_bf16_f32 v77, v22, v23
	v_cvt_pk_bf16_f32 v78, v24, v25
	v_cvt_pk_bf16_f32 v79, v26, v27
	v_cvt_pk_bf16_f32 v80, v28, v29
	v_cvt_pk_bf16_f32 v81, v30, v31
	v_cvt_pk_bf16_f32 v82, v32, v33
	v_cvt_pk_bf16_f32 v83, v34, v35
	ds_write_b128 v2, v[68:71] offset:0
	ds_write_b128 v2, v[72:75] offset:16
	ds_write_b128 v2, v[76:79] offset:32
	ds_write_b128 v2, v[80:83] offset:48
	global_load_dword v4, v1, s[8:9] nt
	s_add_u32 s8, s8, s10
	s_addc_u32 s9, s9, 0
	global_load_dword v5, v1, s[8:9] nt
	s_add_u32 s8, s8, s10
	s_addc_u32 s9, s9, 0
	global_load_dword v6, v1, s[8:9] nt
	s_add_u32 s8, s8, s10
	s_addc_u32 s9, s9, 0
	global_load_dword v7, v1, s[8:9] nt
	s_add_u32 s8, s8, s10
	s_addc_u32 s9, s9, 0
	global_load_dword v8, v1, s[8:9] nt
	s_add_u32 s8, s8, s10
	s_addc_u32 s9, s9, 0
	global_load_dword v9, v1, s[8:9] nt
	s_add_u32 s8, s8, s10
	s_addc_u32 s9, s9, 0
	global_load_dword v10, v1, s[8:9] nt
	s_add_u32 s8, s8, s10
	s_addc_u32 s9, s9, 0
	global_load_dword v11, v1, s[8:9] nt
	s_add_u32 s8, s8, s10
	s_addc_u32 s9, s9, 0
	global_load_dword v12, v1, s[8:9] nt
	s_add_u32 s8, s8, s10
	s_addc_u32 s9, s9, 0
	global_load_dword v13, v1, s[8:9] nt
	s_add_u32 s8, s8, s10
	s_addc_u32 s9, s9, 0
	global_load_dword v14, v1, s[8:9] nt
	s_add_u32 s8, s8, s10
	s_addc_u32 s9, s9, 0
	global_load_dword v15, v1, s[8:9] nt
	s_add_u32 s8, s8, s10
	s_addc_u32 s9, s9, 0
	global_load_dword v16, v1, s[8:9] nt
	s_add_u32 s8, s8, s10
	s_addc_u32 s9, s9, 0
	global_load_dword v17, v1, s[8:9] nt
	s_add_u32 s8, s8, s10
	s_addc_u32 s9, s9, 0
	global_load_dword v18, v1, s[8:9] nt
	s_add_u32 s8, s8, s10
	s_addc_u32 s9, s9, 0
	global_load_dword v19, v1, s[8:9] nt
	s_add_u32 s8, s8, s10
	s_addc_u32 s9, s9, 0
	global_load_dword v20, v1, s[8:9] nt
	s_add_u32 s8, s8, s10
	s_addc_u32 s9, s9, 0
	global_load_dword v21, v1, s[8:9] nt
	s_add_u32 s8, s8, s10
	s_addc_u32 s9, s9, 0
	global_load_dword v22, v1, s[8:9] nt
	s_add_u32 s8, s8, s10
	s_addc_u32 s9, s9, 0
	global_load_dword v23, v1, s[8:9] nt
	s_add_u32 s8, s8, s10
	s_addc_u32 s9, s9, 0
	global_load_dword v24, v1, s[8:9] nt
	s_add_u32 s8, s8, s10
	s_addc_u32 s9, s9, 0
	global_load_dword v25, v1, s[8:9] nt
	s_add_u32 s8, s8, s10
	s_addc_u32 s9, s9, 0
	global_load_dword v26, v1, s[8:9] nt
	s_add_u32 s8, s8, s10
	s_addc_u32 s9, s9, 0
	global_load_dword v27, v1, s[8:9] nt
	s_add_u32 s8, s8, s10
	s_addc_u32 s9, s9, 0
	global_load_dword v28, v1, s[8:9] nt
	s_add_u32 s8, s8, s10
	s_addc_u32 s9, s9, 0
	global_load_dword v29, v1, s[8:9] nt
	s_add_u32 s8, s8, s10
	s_addc_u32 s9, s9, 0
	global_load_dword v30, v1, s[8:9] nt
	s_add_u32 s8, s8, s10
	s_addc_u32 s9, s9, 0
	global_load_dword v31, v1, s[8:9] nt
	s_add_u32 s8, s8, s10
	s_addc_u32 s9, s9, 0
	global_load_dword v32, v1, s[8:9] nt
	s_add_u32 s8, s8, s10
	s_addc_u32 s9, s9, 0
	global_load_dword v33, v1, s[8:9] nt
	s_add_u32 s8, s8, s10
	s_addc_u32 s9, s9, 0
	global_load_dword v34, v1, s[8:9] nt
	s_add_u32 s8, s8, s10
	s_addc_u32 s9, s9, 0
	global_load_dword v35, v1, s[8:9] nt
	s_add_u32 s8, s8, s10
	s_addc_u32 s9, s9, 0
	s_waitcnt vmcnt(40)
	v_cvt_pk_bf16_f32 v100, v36, v37
	v_cvt_pk_bf16_f32 v101, v38, v39
	v_cvt_pk_bf16_f32 v102, v40, v41
	v_cvt_pk_bf16_f32 v103, v42, v43
	v_cvt_pk_bf16_f32 v104, v44, v45
	v_cvt_pk_bf16_f32 v105, v46, v47
	v_cvt_pk_bf16_f32 v106, v48, v49
	v_cvt_pk_bf16_f32 v107, v50, v51
	v_cvt_pk_bf16_f32 v108, v52, v53
	v_cvt_pk_bf16_f32 v109, v54, v55
	v_cvt_pk_bf16_f32 v110, v56, v57
	v_cvt_pk_bf16_f32 v111, v58, v59
	v_cvt_pk_bf16_f32 v112, v60, v61
	v_cvt_pk_bf16_f32 v113, v62, v63
	v_cvt_pk_bf16_f32 v114, v64, v65
	v_cvt_pk_bf16_f32 v115, v66, v67
	ds_write_b128 v2, v[100:103] offset:64
	ds_write_b128 v2, v[104:107] offset:80
	ds_write_b128 v2, v[108:111] offset:96
	ds_write_b128 v2, v[112:115] offset:112
	global_load_dword v36, v1, s[8:9] nt
	s_add_u32 s8, s8, s10
	s_addc_u32 s9, s9, 0
	global_load_dword v37, v1, s[8:9] nt
	s_add_u32 s8, s8, s10
	s_addc_u32 s9, s9, 0
	global_load_dword v38, v1, s[8:9] nt
	s_add_u32 s8, s8, s10
	s_addc_u32 s9, s9, 0
	global_load_dword v39, v1, s[8:9] nt
	s_add_u32 s8, s8, s10
	s_addc_u32 s9, s9, 0
	global_load_dword v40, v1, s[8:9] nt
	s_add_u32 s8, s8, s10
	s_addc_u32 s9, s9, 0
	global_load_dword v41, v1, s[8:9] nt
	s_add_u32 s8, s8, s10
	s_addc_u32 s9, s9, 0
	global_load_dword v42, v1, s[8:9] nt
	s_add_u32 s8, s8, s10
	s_addc_u32 s9, s9, 0
	global_load_dword v43, v1, s[8:9] nt
	s_add_u32 s8, s8, s10
	s_addc_u32 s9, s9, 0
	global_load_dword v44, v1, s[8:9] nt
	s_add_u32 s8, s8, s10
	s_addc_u32 s9, s9, 0
	global_load_dword v45, v1, s[8:9] nt
	s_add_u32 s8, s8, s10
	s_addc_u32 s9, s9, 0
	global_load_dword v46, v1, s[8:9] nt
	s_add_u32 s8, s8, s10
	s_addc_u32 s9, s9, 0
	global_load_dword v47, v1, s[8:9] nt
	s_add_u32 s8, s8, s10
	s_addc_u32 s9, s9, 0
	global_load_dword v48, v1, s[8:9] nt
	s_add_u32 s8, s8, s10
	s_addc_u32 s9, s9, 0
	global_load_dword v49, v1, s[8:9] nt
	s_add_u32 s8, s8, s10
	s_addc_u32 s9, s9, 0
	global_load_dword v50, v1, s[8:9] nt
	s_add_u32 s8, s8, s10
	s_addc_u32 s9, s9, 0
	global_load_dword v51, v1, s[8:9] nt
	s_add_u32 s8, s8, s10
	s_addc_u32 s9, s9, 0
	global_load_dword v52, v1, s[8:9] nt
	s_add_u32 s8, s8, s10
	s_addc_u32 s9, s9, 0
	global_load_dword v53, v1, s[8:9] nt
	s_add_u32 s8, s8, s10
	s_addc_u32 s9, s9, 0
	global_load_dword v54, v1, s[8:9] nt
	s_add_u32 s8, s8, s10
	s_addc_u32 s9, s9, 0
	global_load_dword v55, v1, s[8:9] nt
	s_add_u32 s8, s8, s10
	s_addc_u32 s9, s9, 0
	global_load_dword v56, v1, s[8:9] nt
	s_add_u32 s8, s8, s10
	s_addc_u32 s9, s9, 0
	global_load_dword v57, v1, s[8:9] nt
	s_add_u32 s8, s8, s10
	s_addc_u32 s9, s9, 0
	global_load_dword v58, v1, s[8:9] nt
	s_add_u32 s8, s8, s10
	s_addc_u32 s9, s9, 0
	global_load_dword v59, v1, s[8:9] nt
	s_add_u32 s8, s8, s10
	s_addc_u32 s9, s9, 0
	global_load_dword v60, v1, s[8:9] nt
	s_add_u32 s8, s8, s10
	s_addc_u32 s9, s9, 0
	global_load_dword v61, v1, s[8:9] nt
	s_add_u32 s8, s8, s10
	s_addc_u32 s9, s9, 0
	global_load_dword v62, v1, s[8:9] nt
	s_add_u32 s8, s8, s10
	s_addc_u32 s9, s9, 0
	global_load_dword v63, v1, s[8:9] nt
	s_add_u32 s8, s8, s10
	s_addc_u32 s9, s9, 0
	global_load_dword v64, v1, s[8:9] nt
	s_add_u32 s8, s8, s10
	s_addc_u32 s9, s9, 0
	global_load_dword v65, v1, s[8:9] nt
	s_add_u32 s8, s8, s10
	s_addc_u32 s9, s9, 0
	global_load_dword v66, v1, s[8:9] nt
	s_add_u32 s8, s8, s10
	s_addc_u32 s9, s9, 0
	global_load_dword v67, v1, s[8:9] nt
	s_add_u32 s8, s8, s10
	s_addc_u32 s9, s9, 0
	v_mov_b32_e32 v86, v84
	v_mov_b32_e32 v87, v85
	ds_read_b128 v[116:119], v3 offset:0
	ds_read_b128 v[120:123], v3 offset:1152
	ds_read_b128 v[124:127], v3 offset:2304
	ds_read_b128 v[128:131], v3 offset:3456
	s_waitcnt lgkmcnt(0)
; __device__ __forceinline__ void convert_item(const float* __restrict__ src, int Ksz, int Nsz, u16* __restrict__ dst, int kb, int nb,
;                                              int mode, const int tid) {
;     ...
; #pragma unroll
;     for (int j = 0; j < 64; ++j) v[j] = sp[(size_t)j * Nsz];
;     int nd = n;
;     if (mode == 1) {
;       int isg = n >= 1024, c = n & 1023;
;       nd = (c >> 7) * 256 + isg * 128 + (c & 127);
;     }
;     u32x4* d = reinterpret_cast<u32x4*>(dst + (size_t)nd * Ksz + kb * 64);
; #pragma unroll
;     for (int q = 0; q < 8; ++q) {
;       u32x4 o;
;       o.x = pack2(v[q * 8 + 0], v[q * 8 + 1]);
;       o.y = pack2(v[q * 8 + 2], v[q * 8 + 3]);
;       o.z = pack2(v[q * 8 + 4], v[q * 8 + 5]);
;       o.w = pack2(v[q * 8 + 6], v[q * 8 + 7]);
;       d[q] = o;
;     }
	global_store_dwordx4 v[86:87], v[116:119], off offset:256
	v_lshl_add_u64 v[86:87], v[86:87], 0, s[6:7]
	global_store_dwordx4 v[86:87], v[120:123], off offset:256
	v_lshl_add_u64 v[86:87], v[86:87], 0, s[6:7]
	global_store_dwordx4 v[86:87], v[124:127], off offset:256
	v_lshl_add_u64 v[86:87], v[86:87], 0, s[6:7]
	global_store_dwordx4 v[86:87], v[128:131], off offset:256
	v_lshl_add_u64 v[86:87], v[86:87], 0, s[6:7]
	ds_read_b128 v[116:119], v3 offset:4608
	ds_read_b128 v[120:123], v3 offset:5760
	ds_read_b128 v[124:127], v3 offset:6912
	ds_read_b128 v[128:131], v3 offset:8064
	s_waitcnt lgkmcnt(0)
	global_store_dwordx4 v[86:87], v[116:119], off offset:256
	v_lshl_add_u64 v[86:87], v[86:87], 0, s[6:7]
	global_store_dwordx4 v[86:87], v[120:123], off offset:256
	v_lshl_add_u64 v[86:87], v[86:87], 0, s[6:7]
	global_store_dwordx4 v[86:87], v[124:127], off offset:256
	v_lshl_add_u64 v[86:87], v[86:87], 0, s[6:7]
	global_store_dwordx4 v[86:87], v[128:131], off offset:256
	v_lshl_add_u64 v[86:87], v[86:87], 0, s[6:7]
	s_waitcnt vmcnt(40)
	v_cvt_pk_bf16_f32 v68, v4, v5
	v_cvt_pk_bf16_f32 v69, v6, v7
	v_cvt_pk_bf16_f32 v70, v8, v9
	v_cvt_pk_bf16_f32 v71, v10, v11
	v_cvt_pk_bf16_f32 v72, v12, v13
	v_cvt_pk_bf16_f32 v73, v14, v15
	v_cvt_pk_bf16_f32 v74, v16, v17
	v_cvt_pk_bf16_f32 v75, v18, v19
	v_cvt_pk_bf16_f32 v76, v20, v21
	v_cvt_pk_bf16_f32 v77, v22, v23
	v_cvt_pk_bf16_f32 v78, v24, v25
	v_cvt_pk_bf16_f32 v79, v26, v27
	v_cvt_pk_bf16_f32 v80, v28, v29
	v_cvt_pk_bf16_f32 v81, v30, v31
	v_cvt_pk_bf16_f32 v82, v32, v33
	v_cvt_pk_bf16_f32 v83, v34, v35
	ds_write_b128 v2, v[68:71] offset:0
	ds_write_b128 v2, v[72:75] offset:16
	ds_write_b128 v2, v[76:79] offset:32
	ds_write_b128 v2, v[80:83] offset:48
	s_waitcnt vmcnt(8)
	v_cvt_pk_bf16_f32 v100, v36, v37
	v_cvt_pk_bf16_f32 v101, v38, v39
	v_cvt_pk_bf16_f32 v102, v40, v41
	v_cvt_pk_bf16_f32 v103, v42, v43
	v_cvt_pk_bf16_f32 v104, v44, v45
	v_cvt_pk_bf16_f32 v105, v46, v47
	v_cvt_pk_bf16_f32 v106, v48, v49
	v_cvt_pk_bf16_f32 v107, v50, v51
	v_cvt_pk_bf16_f32 v108, v52, v53
	v_cvt_pk_bf16_f32 v109, v54, v55
	v_cvt_pk_bf16_f32 v110, v56, v57
	v_cvt_pk_bf16_f32 v111, v58, v59
	v_cvt_pk_bf16_f32 v112, v60, v61
	v_cvt_pk_bf16_f32 v113, v62, v63
	v_cvt_pk_bf16_f32 v114, v64, v65
	v_cvt_pk_bf16_f32 v115, v66, v67
	ds_write_b128 v2, v[100:103] offset:64
	ds_write_b128 v2, v[104:107] offset:80
	ds_write_b128 v2, v[108:111] offset:96
	ds_write_b128 v2, v[112:115] offset:112
	v_mov_b32_e32 v86, v84
	v_mov_b32_e32 v87, v85
	ds_read_b128 v[116:119], v3 offset:0
	ds_read_b128 v[120:123], v3 offset:1152
	ds_read_b128 v[124:127], v3 offset:2304
	ds_read_b128 v[128:131], v3 offset:3456
	s_waitcnt lgkmcnt(0)
	global_store_dwordx4 v[86:87], v[116:119], off offset:384
	v_lshl_add_u64 v[86:87], v[86:87], 0, s[6:7]
	global_store_dwordx4 v[86:87], v[120:123], off offset:384
	v_lshl_add_u64 v[86:87], v[86:87], 0, s[6:7]
	global_store_dwordx4 v[86:87], v[124:127], off offset:384
	v_lshl_add_u64 v[86:87], v[86:87], 0, s[6:7]
	global_store_dwordx4 v[86:87], v[128:131], off offset:384
	v_lshl_add_u64 v[86:87], v[86:87], 0, s[6:7]
	ds_read_b128 v[116:119], v3 offset:4608
	ds_read_b128 v[120:123], v3 offset:5760
	ds_read_b128 v[124:127], v3 offset:6912
	ds_read_b128 v[128:131], v3 offset:8064
	s_waitcnt lgkmcnt(0)
	global_store_dwordx4 v[86:87], v[116:119], off offset:384
	v_lshl_add_u64 v[86:87], v[86:87], 0, s[6:7]
	global_store_dwordx4 v[86:87], v[120:123], off offset:384
	v_lshl_add_u64 v[86:87], v[86:87], 0, s[6:7]
	global_store_dwordx4 v[86:87], v[124:127], off offset:384
	v_lshl_add_u64 v[86:87], v[86:87], 0, s[6:7]
	global_store_dwordx4 v[86:87], v[128:131], off offset:384
	v_lshl_add_u64 v[86:87], v[86:87], 0, s[6:7]
